# prompt pooling units: fast path with all window rows loaded up front (31 / 19 loads in flight), counted vmcnt, v_cvt_pk_bf16 packing
# speedup vs baseline: 1.0325x; 1.0156x over previous
; #define GAS __attribute__((address_space(1)))
; __device__ __forceinline__ unsigned pk2(float lo, float hi) { return f2bf(lo) | (f2bf(hi) << 16); }
; #define WSB(F, off) ((bf16*)(wsq((F).ws) + (off)))
; __device__ __forceinline__ TC thread_coords(int wave) { TC c; int l = lane_id_(); asm volatile("" : "+v"(l)); c.lane = l; c.wave = wave; c.tid = wave * 64 + l; return c; }
; __device__ __forceinline__ void pool_unit(const Frame& F, int layer, int uid) {
;     ...
;     if (uid < 1024) { stream = 0; b = uid >> 5; t0 = (uid & 31) * 64; Tlen = T; rowbase = b * T; }
;     else if (uid < 1032) { stream = 1; b = uid - 1024; t0 = 0; Tlen = ST; rowbase = ROW_S + b * ST; }
;     else { stream = 2; b = 0; t0 = 0; Tlen = NMETA; rowbase = ROW_M; }
;     const TC tc = thread_coords(F.wave); const int ch = tc.tid & 127, tsub = tc.tid >> 7, win = 2 << (ch >> 5);
;     const int ts = t0 + tsub * 16; if (ts >= Tlen) return;
;     float acc[8];
; #pragma unroll
;     for (int e = 0; e < 8; ++e) acc[e] = 0.f;
; #pragma unroll
;     for (int j = 1; j < 16; ++j) if (j < win) { float v[8]; pool_row(F, layer, stream, b, rowbase, ts - j, ch, v);
; #pragma unroll
;         for (int e = 0; e < 8; ++e) acc[e] += v[e]; }
; #pragma unroll 4
;     for (int tt = 0; tt < 16; ++tt) {
;         const int t = ts + tt;
;         float vn[8], vo[8]; pool_row(F, layer, stream, b, rowbase, t, ch, vn);
;         if (tt > 0) pool_row(F, layer, stream, b, rowbase, t - win, ch, vo);
; #pragma unroll
;         for (int e = 0; e < 8; ++e) acc[e] += vn[e] - (tt > 0 ? vo[e] : 0.f);
;         const int have = (stream == 2) ? (t + 1 < win ? t + 1 : win) : win;
;         const float inv = 1.0f / (float)have;
;         float y[8];
; #pragma unroll
;         for (int e = 0; e < 8; ++e) y[e] = acc[e] * inv - vn[e];
;         *(GAS v4u*)(WSB(F, WS_BR) + (size_t)2 * M_PAD * D + (size_t)(rowbase + t) * D + ch * 8) = (v4u){pk2(y[0], y[1]), pk2(y[2], y[3]), pk2(y[4], y[5]), pk2(y[6], y[7])};
.LBB0_1193:
	s_and_b64 vcc, exec, s[18:19]
	s_cbranch_vccz .LBB0_1354
	s_cmp_eq_u32 s3, 1
	s_cbranch_scc1 .Lpool_small_rows
	v_mbcnt_lo_u32_b32 v1, -1, 0
	v_mbcnt_hi_u32_b32 v1, -1, v1
	s_lshr_b32 s8, s5, 5
	s_and_b32 s9, s5, 31
	s_lshl_b32 s9, s9, 6
	s_lshr_b32 s10, s85, 7
	s_lshl_b32 s10, s10, 4
	s_add_i32 s10, s10, s9
	s_lshl_b32 s11, s8, 11
	s_add_i32 s11, s11, s10
	s_cmp_eq_u32 s10, 0
	s_cselect_b32 s12, 0x10110, s11
	v_add_u32_e32 v2, s85, v1
	v_and_b32_e32 v3, 0x7f, v2
	v_lshlrev_b32_e32 v3, 4, v3
	s_add_u32 s14, s46, 0x56bc0000
	s_addc_u32 s15, s47, 0
	s_add_u32 s16, s46, 0x871c0000
	s_addc_u32 s17, s47, 0
	s_lshr_b32 s19, s11, 21
	s_lshl_b32 s18, s11, 11
	s_add_u32 s22, s16, s18
	s_addc_u32 s23, s17, s19
	s_add_u32 s18, s14, s18
	s_addc_u32 s19, s15, s19
	s_lshr_b32 s21, s12, 21
	s_lshl_b32 s20, s12, 11
	s_add_u32 s20, s14, s20
	s_addc_u32 s21, s15, s21
	s_mov_b32 s28, -1
	s_mov_b32 s29, 0
	s_mov_b32 s30, 0
	s_mov_b32 s31, -1
	s_bitcmp1_b32 s85, 6
	s_cbranch_scc1 .Lpool_fast_wide
	v_mov_b32_e32 v4, 0x3f000000
	v_mov_b32_e32 v6, 0x3e800000
	v_cmp_gt_u32_e32 vcc, 32, v1
	s_nop 1
	v_cndmask_b32_e32 v4, v6, v4, vcc
	v_mov_b32_e32 v5, v4
	s_sub_u32 s24, s20, 0x1000
	s_subb_u32 s25, s21, 0
	global_load_dwordx4 v[76:79], v3, s[24:25] offset:2048
	global_load_dwordx4 v[72:75], v3, s[24:25]
	s_sub_u32 s24, s20, 0x1800
	s_subb_u32 s25, s21, 0
	global_load_dwordx4 v[68:71], v3, s[24:25]
	s_mov_b64 s[24:25], s[18:19]
	global_load_dwordx4 v[80:83], v3, s[24:25]
	global_load_dwordx4 v[84:87], v3, s[24:25] offset:2048
	s_add_u32 s24, s18, 0x1000
	s_addc_u32 s25, s19, 0
	global_load_dwordx4 v[88:91], v3, s[24:25]
	global_load_dwordx4 v[92:95], v3, s[24:25] offset:2048
	s_add_u32 s24, s18, 0x2000
	s_addc_u32 s25, s19, 0
	global_load_dwordx4 v[96:99], v3, s[24:25]
	global_load_dwordx4 v[100:103], v3, s[24:25] offset:2048
	s_add_u32 s24, s18, 0x3000
	s_addc_u32 s25, s19, 0
	global_load_dwordx4 v[104:107], v3, s[24:25]
	global_load_dwordx4 v[108:111], v3, s[24:25] offset:2048
	s_add_u32 s24, s18, 0x4000
	s_addc_u32 s25, s19, 0
	global_load_dwordx4 v[112:115], v3, s[24:25]
	global_load_dwordx4 v[116:119], v3, s[24:25] offset:2048
	s_add_u32 s24, s18, 0x5000
	s_addc_u32 s25, s19, 0
	global_load_dwordx4 v[120:123], v3, s[24:25]
	global_load_dwordx4 v[124:127], v3, s[24:25] offset:2048
	s_add_u32 s24, s18, 0x6000
	s_addc_u32 s25, s19, 0
	global_load_dwordx4 v[128:131], v3, s[24:25]
	global_load_dwordx4 v[132:135], v3, s[24:25] offset:2048
	s_add_u32 s24, s18, 0x7000
	s_addc_u32 s25, s19, 0
	global_load_dwordx4 v[136:139], v3, s[24:25]
	global_load_dwordx4 v[140:143], v3, s[24:25] offset:2048
	v_mov_b32_e32 v8, 0
	v_mov_b32_e32 v9, 0
	v_mov_b32_e32 v10, 0
	v_mov_b32_e32 v11, 0
	v_mov_b32_e32 v12, 0
	v_mov_b32_e32 v13, 0
	v_mov_b32_e32 v14, 0
	v_mov_b32_e32 v15, 0
	s_waitcnt vmcnt(18)
	v_lshlrev_b32_e32 v152, 16, v76
	v_and_b32_e32 v153, 0xffff0000, v76
	v_lshlrev_b32_e32 v154, 16, v77
	v_and_b32_e32 v155, 0xffff0000, v77
	v_lshlrev_b32_e32 v156, 16, v78
	v_and_b32_e32 v157, 0xffff0000, v78
	v_lshlrev_b32_e32 v158, 16, v79
	v_and_b32_e32 v159, 0xffff0000, v79
	v_pk_add_f32 v[8:9], v[8:9], v[152:153]
	v_pk_add_f32 v[10:11], v[10:11], v[154:155]
	v_pk_add_f32 v[12:13], v[12:13], v[156:157]
	v_pk_add_f32 v[14:15], v[14:15], v[158:159]
	s_waitcnt vmcnt(17)
	v_lshlrev_b32_e32 v152, 16, v72
	v_and_b32_e32 v153, 0xffff0000, v72
	v_lshlrev_b32_e32 v154, 16, v73
	v_and_b32_e32 v155, 0xffff0000, v73
	v_lshlrev_b32_e32 v156, 16, v74
	v_and_b32_e32 v157, 0xffff0000, v74
	v_lshlrev_b32_e32 v158, 16, v75
	v_and_b32_e32 v159, 0xffff0000, v75
	s_mov_b64 exec, s[30:31]
	v_pk_add_f32 v[8:9], v[8:9], v[152:153]
	v_pk_add_f32 v[10:11], v[10:11], v[154:155]
	v_pk_add_f32 v[12:13], v[12:13], v[156:157]
	v_pk_add_f32 v[14:15], v[14:15], v[158:159]
	s_mov_b64 exec, -1
	s_waitcnt vmcnt(16)
	v_lshlrev_b32_e32 v152, 16, v68
	v_and_b32_e32 v153, 0xffff0000, v68
	v_lshlrev_b32_e32 v154, 16, v69
	v_and_b32_e32 v155, 0xffff0000, v69
	v_lshlrev_b32_e32 v156, 16, v70
	v_and_b32_e32 v157, 0xffff0000, v70
	v_lshlrev_b32_e32 v158, 16, v71
	v_and_b32_e32 v159, 0xffff0000, v71
	s_mov_b64 exec, s[30:31]
	v_pk_add_f32 v[8:9], v[8:9], v[152:153]
	v_pk_add_f32 v[10:11], v[10:11], v[154:155]
	v_pk_add_f32 v[12:13], v[12:13], v[156:157]
	v_pk_add_f32 v[14:15], v[14:15], v[158:159]
	s_mov_b64 exec, -1
	s_waitcnt vmcnt(15)
	v_lshlrev_b32_e32 v144, 16, v80
	v_and_b32_e32 v145, 0xffff0000, v80
	v_lshlrev_b32_e32 v146, 16, v81
	v_and_b32_e32 v147, 0xffff0000, v81
	v_lshlrev_b32_e32 v148, 16, v82
	v_and_b32_e32 v149, 0xffff0000, v82
	v_lshlrev_b32_e32 v150, 16, v83
	v_and_b32_e32 v151, 0xffff0000, v83
	v_pk_add_f32 v[8:9], v[8:9], v[144:145]
	v_pk_add_f32 v[10:11], v[10:11], v[146:147]
	v_pk_add_f32 v[12:13], v[12:13], v[148:149]
	v_pk_add_f32 v[14:15], v[14:15], v[150:151]
	v_pk_fma_f32 v[168:169], v[8:9], v[4:5], v[144:145] neg_lo:[0,0,1] neg_hi:[0,0,1]
	v_pk_fma_f32 v[170:171], v[10:11], v[4:5], v[146:147] neg_lo:[0,0,1] neg_hi:[0,0,1]
	v_pk_fma_f32 v[172:173], v[12:13], v[4:5], v[148:149] neg_lo:[0,0,1] neg_hi:[0,0,1]
	v_pk_fma_f32 v[174:175], v[14:15], v[4:5], v[150:151] neg_lo:[0,0,1] neg_hi:[0,0,1]
	v_cvt_pk_bf16_f32 v176, v168, v169
	v_cvt_pk_bf16_f32 v177, v170, v171
	v_cvt_pk_bf16_f32 v178, v172, v173
	v_cvt_pk_bf16_f32 v179, v174, v175
	s_mov_b64 s[26:27], s[22:23]
	s_nop 0
	global_store_dwordx4 v3, v[176:179], s[26:27]
	s_nop 1
	s_waitcnt vmcnt(15)
; #define GAS __attribute__((address_space(1)))
; __device__ __forceinline__ unsigned pk2(float lo, float hi) { return f2bf(lo) | (f2bf(hi) << 16); }
; #define WSB(F, off) ((bf16*)(wsq((F).ws) + (off)))
; __device__ __forceinline__ void pool_unit(const Frame& F, int layer, int uid) {
;     ...
;     for (int tt = 0; tt < 16; ++tt) {
;         const int t = ts + tt;
;         float vn[8], vo[8]; pool_row(F, layer, stream, b, rowbase, t, ch, vn);
;         if (tt > 0) pool_row(F, layer, stream, b, rowbase, t - win, ch, vo);
; #pragma unroll
;         for (int e = 0; e < 8; ++e) acc[e] += vn[e] - (tt > 0 ? vo[e] : 0.f);
;         const int have = (stream == 2) ? (t + 1 < win ? t + 1 : win) : win;
;         const float inv = 1.0f / (float)have;
;         float y[8];
; #pragma unroll
;         for (int e = 0; e < 8; ++e) y[e] = acc[e] * inv - vn[e];
;         *(GAS v4u*)(WSB(F, WS_BR) + (size_t)2 * M_PAD * D + (size_t)(rowbase + t) * D + ch * 8) = (v4u){pk2(y[0], y[1]), pk2(y[2], y[3]), pk2(y[4], y[5]), pk2(y[6], y[7])};
	v_lshlrev_b32_e32 v144, 16, v84
	v_and_b32_e32 v145, 0xffff0000, v84
	v_lshlrev_b32_e32 v146, 16, v85
	v_and_b32_e32 v147, 0xffff0000, v85
	v_lshlrev_b32_e32 v148, 16, v86
	v_and_b32_e32 v149, 0xffff0000, v86
	v_lshlrev_b32_e32 v150, 16, v87
	v_and_b32_e32 v151, 0xffff0000, v87
	v_lshlrev_b32_e32 v152, 16, v76
	v_and_b32_e32 v153, 0xffff0000, v76
	v_lshlrev_b32_e32 v154, 16, v77
	v_and_b32_e32 v155, 0xffff0000, v77
	v_lshlrev_b32_e32 v156, 16, v78
	v_and_b32_e32 v157, 0xffff0000, v78
	v_lshlrev_b32_e32 v158, 16, v79
	v_and_b32_e32 v159, 0xffff0000, v79
	s_mov_b64 exec, s[28:29]
	v_pk_add_f32 v[160:161], v[144:145], v[152:153] neg_lo:[0,1] neg_hi:[0,1]
	v_pk_add_f32 v[162:163], v[146:147], v[154:155] neg_lo:[0,1] neg_hi:[0,1]
	v_pk_add_f32 v[164:165], v[148:149], v[156:157] neg_lo:[0,1] neg_hi:[0,1]
	v_pk_add_f32 v[166:167], v[150:151], v[158:159] neg_lo:[0,1] neg_hi:[0,1]
	s_mov_b64 exec, -1
	v_lshlrev_b32_e32 v152, 16, v68
	v_and_b32_e32 v153, 0xffff0000, v68
	v_lshlrev_b32_e32 v154, 16, v69
	v_and_b32_e32 v155, 0xffff0000, v69
	v_lshlrev_b32_e32 v156, 16, v70
	v_and_b32_e32 v157, 0xffff0000, v70
	v_lshlrev_b32_e32 v158, 16, v71
	v_and_b32_e32 v159, 0xffff0000, v71
	s_mov_b64 exec, s[30:31]
	v_pk_add_f32 v[160:161], v[144:145], v[152:153] neg_lo:[0,1] neg_hi:[0,1]
	v_pk_add_f32 v[162:163], v[146:147], v[154:155] neg_lo:[0,1] neg_hi:[0,1]
	v_pk_add_f32 v[164:165], v[148:149], v[156:157] neg_lo:[0,1] neg_hi:[0,1]
	v_pk_add_f32 v[166:167], v[150:151], v[158:159] neg_lo:[0,1] neg_hi:[0,1]
	s_mov_b64 exec, -1
	v_pk_add_f32 v[8:9], v[8:9], v[160:161]
	v_pk_add_f32 v[10:11], v[10:11], v[162:163]
	v_pk_add_f32 v[12:13], v[12:13], v[164:165]
	v_pk_add_f32 v[14:15], v[14:15], v[166:167]
	v_pk_fma_f32 v[168:169], v[8:9], v[4:5], v[144:145] neg_lo:[0,0,1] neg_hi:[0,0,1]
	v_pk_fma_f32 v[170:171], v[10:11], v[4:5], v[146:147] neg_lo:[0,0,1] neg_hi:[0,0,1]
	v_pk_fma_f32 v[172:173], v[12:13], v[4:5], v[148:149] neg_lo:[0,0,1] neg_hi:[0,0,1]
	v_pk_fma_f32 v[174:175], v[14:15], v[4:5], v[150:151] neg_lo:[0,0,1] neg_hi:[0,0,1]
	v_cvt_pk_bf16_f32 v176, v168, v169
	v_cvt_pk_bf16_f32 v177, v170, v171
	v_cvt_pk_bf16_f32 v178, v172, v173
	v_cvt_pk_bf16_f32 v179, v174, v175
	s_nop 0
	global_store_dwordx4 v3, v[176:179], s[26:27] offset:2048
	s_nop 1
	s_waitcnt vmcnt(15)
	v_lshlrev_b32_e32 v144, 16, v88
	v_and_b32_e32 v145, 0xffff0000, v88
	v_lshlrev_b32_e32 v146, 16, v89
	v_and_b32_e32 v147, 0xffff0000, v89
	v_lshlrev_b32_e32 v148, 16, v90
	v_and_b32_e32 v149, 0xffff0000, v90
	v_lshlrev_b32_e32 v150, 16, v91
	v_and_b32_e32 v151, 0xffff0000, v91
	v_lshlrev_b32_e32 v152, 16, v80
	v_and_b32_e32 v153, 0xffff0000, v80
	v_lshlrev_b32_e32 v154, 16, v81
	v_and_b32_e32 v155, 0xffff0000, v81
	v_lshlrev_b32_e32 v156, 16, v82
	v_and_b32_e32 v157, 0xffff0000, v82
	v_lshlrev_b32_e32 v158, 16, v83
	v_and_b32_e32 v159, 0xffff0000, v83
	s_mov_b64 exec, s[28:29]
	v_pk_add_f32 v[160:161], v[144:145], v[152:153] neg_lo:[0,1] neg_hi:[0,1]
	v_pk_add_f32 v[162:163], v[146:147], v[154:155] neg_lo:[0,1] neg_hi:[0,1]
	v_pk_add_f32 v[164:165], v[148:149], v[156:157] neg_lo:[0,1] neg_hi:[0,1]
	v_pk_add_f32 v[166:167], v[150:151], v[158:159] neg_lo:[0,1] neg_hi:[0,1]
	s_mov_b64 exec, -1
	v_lshlrev_b32_e32 v152, 16, v72
	v_and_b32_e32 v153, 0xffff0000, v72
	v_lshlrev_b32_e32 v154, 16, v73
	v_and_b32_e32 v155, 0xffff0000, v73
	v_lshlrev_b32_e32 v156, 16, v74
	v_and_b32_e32 v157, 0xffff0000, v74
	v_lshlrev_b32_e32 v158, 16, v75
	v_and_b32_e32 v159, 0xffff0000, v75
	s_mov_b64 exec, s[30:31]
	v_pk_add_f32 v[160:161], v[144:145], v[152:153] neg_lo:[0,1] neg_hi:[0,1]
	v_pk_add_f32 v[162:163], v[146:147], v[154:155] neg_lo:[0,1] neg_hi:[0,1]
	v_pk_add_f32 v[164:165], v[148:149], v[156:157] neg_lo:[0,1] neg_hi:[0,1]
	v_pk_add_f32 v[166:167], v[150:151], v[158:159] neg_lo:[0,1] neg_hi:[0,1]
	s_mov_b64 exec, -1
	v_pk_add_f32 v[8:9], v[8:9], v[160:161]
	v_pk_add_f32 v[10:11], v[10:11], v[162:163]
	v_pk_add_f32 v[12:13], v[12:13], v[164:165]
	v_pk_add_f32 v[14:15], v[14:15], v[166:167]
	v_pk_fma_f32 v[168:169], v[8:9], v[4:5], v[144:145] neg_lo:[0,0,1] neg_hi:[0,0,1]
	v_pk_fma_f32 v[170:171], v[10:11], v[4:5], v[146:147] neg_lo:[0,0,1] neg_hi:[0,0,1]
	v_pk_fma_f32 v[172:173], v[12:13], v[4:5], v[148:149] neg_lo:[0,0,1] neg_hi:[0,0,1]
	v_pk_fma_f32 v[174:175], v[14:15], v[4:5], v[150:151] neg_lo:[0,0,1] neg_hi:[0,0,1]
	v_cvt_pk_bf16_f32 v176, v168, v169
	v_cvt_pk_bf16_f32 v177, v170, v171
	v_cvt_pk_bf16_f32 v178, v172, v173
	v_cvt_pk_bf16_f32 v179, v174, v175
	s_add_u32 s26, s22, 0x1000
	s_addc_u32 s27, s23, 0
	s_nop 0
	global_store_dwordx4 v3, v[176:179], s[26:27]
	s_nop 1
	s_waitcnt vmcnt(15)
; #define GAS __attribute__((address_space(1)))
; __device__ __forceinline__ unsigned pk2(float lo, float hi) { return f2bf(lo) | (f2bf(hi) << 16); }
; #define WSB(F, off) ((bf16*)(wsq((F).ws) + (off)))
; __device__ __forceinline__ void pool_unit(const Frame& F, int layer, int uid) {
;     ...
;     for (int tt = 0; tt < 16; ++tt) {
;         const int t = ts + tt;
;         float vn[8], vo[8]; pool_row(F, layer, stream, b, rowbase, t, ch, vn);
;         if (tt > 0) pool_row(F, layer, stream, b, rowbase, t - win, ch, vo);
; #pragma unroll
;         for (int e = 0; e < 8; ++e) acc[e] += vn[e] - (tt > 0 ? vo[e] : 0.f);
;         const int have = (stream == 2) ? (t + 1 < win ? t + 1 : win) : win;
;         const float inv = 1.0f / (float)have;
;         float y[8];
; #pragma unroll
;         for (int e = 0; e < 8; ++e) y[e] = acc[e] * inv - vn[e];
;         *(GAS v4u*)(WSB(F, WS_BR) + (size_t)2 * M_PAD * D + (size_t)(rowbase + t) * D + ch * 8) = (v4u){pk2(y[0], y[1]), pk2(y[2], y[3]), pk2(y[4], y[5]), pk2(y[6], y[7])};
	v_lshlrev_b32_e32 v144, 16, v92
	v_and_b32_e32 v145, 0xffff0000, v92
	v_lshlrev_b32_e32 v146, 16, v93
	v_and_b32_e32 v147, 0xffff0000, v93
	v_lshlrev_b32_e32 v148, 16, v94
	v_and_b32_e32 v149, 0xffff0000, v94
	v_lshlrev_b32_e32 v150, 16, v95
	v_and_b32_e32 v151, 0xffff0000, v95
	v_lshlrev_b32_e32 v152, 16, v84
	v_and_b32_e32 v153, 0xffff0000, v84
	v_lshlrev_b32_e32 v154, 16, v85
	v_and_b32_e32 v155, 0xffff0000, v85
	v_lshlrev_b32_e32 v156, 16, v86
	v_and_b32_e32 v157, 0xffff0000, v86
	v_lshlrev_b32_e32 v158, 16, v87
	v_and_b32_e32 v159, 0xffff0000, v87
	s_mov_b64 exec, s[28:29]
	v_pk_add_f32 v[160:161], v[144:145], v[152:153] neg_lo:[0,1] neg_hi:[0,1]
	v_pk_add_f32 v[162:163], v[146:147], v[154:155] neg_lo:[0,1] neg_hi:[0,1]
	v_pk_add_f32 v[164:165], v[148:149], v[156:157] neg_lo:[0,1] neg_hi:[0,1]
	v_pk_add_f32 v[166:167], v[150:151], v[158:159] neg_lo:[0,1] neg_hi:[0,1]
	s_mov_b64 exec, -1
	v_lshlrev_b32_e32 v152, 16, v76
	v_and_b32_e32 v153, 0xffff0000, v76
	v_lshlrev_b32_e32 v154, 16, v77
	v_and_b32_e32 v155, 0xffff0000, v77
	v_lshlrev_b32_e32 v156, 16, v78
	v_and_b32_e32 v157, 0xffff0000, v78
	v_lshlrev_b32_e32 v158, 16, v79
	v_and_b32_e32 v159, 0xffff0000, v79
	s_mov_b64 exec, s[30:31]
	v_pk_add_f32 v[160:161], v[144:145], v[152:153] neg_lo:[0,1] neg_hi:[0,1]
	v_pk_add_f32 v[162:163], v[146:147], v[154:155] neg_lo:[0,1] neg_hi:[0,1]
	v_pk_add_f32 v[164:165], v[148:149], v[156:157] neg_lo:[0,1] neg_hi:[0,1]
	v_pk_add_f32 v[166:167], v[150:151], v[158:159] neg_lo:[0,1] neg_hi:[0,1]
	s_mov_b64 exec, -1
	v_pk_add_f32 v[8:9], v[8:9], v[160:161]
	v_pk_add_f32 v[10:11], v[10:11], v[162:163]
	v_pk_add_f32 v[12:13], v[12:13], v[164:165]
	v_pk_add_f32 v[14:15], v[14:15], v[166:167]
	v_pk_fma_f32 v[168:169], v[8:9], v[4:5], v[144:145] neg_lo:[0,0,1] neg_hi:[0,0,1]
	v_pk_fma_f32 v[170:171], v[10:11], v[4:5], v[146:147] neg_lo:[0,0,1] neg_hi:[0,0,1]
	v_pk_fma_f32 v[172:173], v[12:13], v[4:5], v[148:149] neg_lo:[0,0,1] neg_hi:[0,0,1]
	v_pk_fma_f32 v[174:175], v[14:15], v[4:5], v[150:151] neg_lo:[0,0,1] neg_hi:[0,0,1]
	v_cvt_pk_bf16_f32 v176, v168, v169
	v_cvt_pk_bf16_f32 v177, v170, v171
	v_cvt_pk_bf16_f32 v178, v172, v173
	v_cvt_pk_bf16_f32 v179, v174, v175
	s_nop 0
	global_store_dwordx4 v3, v[176:179], s[26:27] offset:2048
	s_nop 1
	s_waitcnt vmcnt(15)
	v_lshlrev_b32_e32 v144, 16, v96
	v_and_b32_e32 v145, 0xffff0000, v96
	v_lshlrev_b32_e32 v146, 16, v97
	v_and_b32_e32 v147, 0xffff0000, v97
	v_lshlrev_b32_e32 v148, 16, v98
	v_and_b32_e32 v149, 0xffff0000, v98
	v_lshlrev_b32_e32 v150, 16, v99
	v_and_b32_e32 v151, 0xffff0000, v99
	v_lshlrev_b32_e32 v152, 16, v88
	v_and_b32_e32 v153, 0xffff0000, v88
	v_lshlrev_b32_e32 v154, 16, v89
	v_and_b32_e32 v155, 0xffff0000, v89
	v_lshlrev_b32_e32 v156, 16, v90
	v_and_b32_e32 v157, 0xffff0000, v90
	v_lshlrev_b32_e32 v158, 16, v91
	v_and_b32_e32 v159, 0xffff0000, v91
	s_mov_b64 exec, s[28:29]
	v_pk_add_f32 v[160:161], v[144:145], v[152:153] neg_lo:[0,1] neg_hi:[0,1]
	v_pk_add_f32 v[162:163], v[146:147], v[154:155] neg_lo:[0,1] neg_hi:[0,1]
	v_pk_add_f32 v[164:165], v[148:149], v[156:157] neg_lo:[0,1] neg_hi:[0,1]
	v_pk_add_f32 v[166:167], v[150:151], v[158:159] neg_lo:[0,1] neg_hi:[0,1]
	s_mov_b64 exec, -1
	v_lshlrev_b32_e32 v152, 16, v80
	v_and_b32_e32 v153, 0xffff0000, v80
	v_lshlrev_b32_e32 v154, 16, v81
	v_and_b32_e32 v155, 0xffff0000, v81
	v_lshlrev_b32_e32 v156, 16, v82
	v_and_b32_e32 v157, 0xffff0000, v82
	v_lshlrev_b32_e32 v158, 16, v83
	v_and_b32_e32 v159, 0xffff0000, v83
	s_mov_b64 exec, s[30:31]
	v_pk_add_f32 v[160:161], v[144:145], v[152:153] neg_lo:[0,1] neg_hi:[0,1]
	v_pk_add_f32 v[162:163], v[146:147], v[154:155] neg_lo:[0,1] neg_hi:[0,1]
	v_pk_add_f32 v[164:165], v[148:149], v[156:157] neg_lo:[0,1] neg_hi:[0,1]
	v_pk_add_f32 v[166:167], v[150:151], v[158:159] neg_lo:[0,1] neg_hi:[0,1]
	s_mov_b64 exec, -1
	v_pk_add_f32 v[8:9], v[8:9], v[160:161]
	v_pk_add_f32 v[10:11], v[10:11], v[162:163]
	v_pk_add_f32 v[12:13], v[12:13], v[164:165]
	v_pk_add_f32 v[14:15], v[14:15], v[166:167]
	v_pk_fma_f32 v[168:169], v[8:9], v[4:5], v[144:145] neg_lo:[0,0,1] neg_hi:[0,0,1]
	v_pk_fma_f32 v[170:171], v[10:11], v[4:5], v[146:147] neg_lo:[0,0,1] neg_hi:[0,0,1]
	v_pk_fma_f32 v[172:173], v[12:13], v[4:5], v[148:149] neg_lo:[0,0,1] neg_hi:[0,0,1]
	v_pk_fma_f32 v[174:175], v[14:15], v[4:5], v[150:151] neg_lo:[0,0,1] neg_hi:[0,0,1]
	v_cvt_pk_bf16_f32 v176, v168, v169
	v_cvt_pk_bf16_f32 v177, v170, v171
	v_cvt_pk_bf16_f32 v178, v172, v173
	v_cvt_pk_bf16_f32 v179, v174, v175
	s_add_u32 s26, s22, 0x2000
	s_addc_u32 s27, s23, 0
	s_nop 0
	global_store_dwordx4 v3, v[176:179], s[26:27]
	s_nop 1
	s_waitcnt vmcnt(15)
; #define GAS __attribute__((address_space(1)))
; __device__ __forceinline__ unsigned pk2(float lo, float hi) { return f2bf(lo) | (f2bf(hi) << 16); }
; #define WSB(F, off) ((bf16*)(wsq((F).ws) + (off)))
; __device__ __forceinline__ void pool_unit(const Frame& F, int layer, int uid) {
;     ...
;     for (int tt = 0; tt < 16; ++tt) {
;         const int t = ts + tt;
;         float vn[8], vo[8]; pool_row(F, layer, stream, b, rowbase, t, ch, vn);
;         if (tt > 0) pool_row(F, layer, stream, b, rowbase, t - win, ch, vo);
; #pragma unroll
;         for (int e = 0; e < 8; ++e) acc[e] += vn[e] - (tt > 0 ? vo[e] : 0.f);
;         const int have = (stream == 2) ? (t + 1 < win ? t + 1 : win) : win;
;         const float inv = 1.0f / (float)have;
;         float y[8];
; #pragma unroll
;         for (int e = 0; e < 8; ++e) y[e] = acc[e] * inv - vn[e];
;         *(GAS v4u*)(WSB(F, WS_BR) + (size_t)2 * M_PAD * D + (size_t)(rowbase + t) * D + ch * 8) = (v4u){pk2(y[0], y[1]), pk2(y[2], y[3]), pk2(y[4], y[5]), pk2(y[6], y[7])};
	v_lshlrev_b32_e32 v144, 16, v100
	v_and_b32_e32 v145, 0xffff0000, v100
	v_lshlrev_b32_e32 v146, 16, v101
	v_and_b32_e32 v147, 0xffff0000, v101
	v_lshlrev_b32_e32 v148, 16, v102
	v_and_b32_e32 v149, 0xffff0000, v102
	v_lshlrev_b32_e32 v150, 16, v103
	v_and_b32_e32 v151, 0xffff0000, v103
	v_lshlrev_b32_e32 v152, 16, v92
	v_and_b32_e32 v153, 0xffff0000, v92
	v_lshlrev_b32_e32 v154, 16, v93
	v_and_b32_e32 v155, 0xffff0000, v93
	v_lshlrev_b32_e32 v156, 16, v94
	v_and_b32_e32 v157, 0xffff0000, v94
	v_lshlrev_b32_e32 v158, 16, v95
	v_and_b32_e32 v159, 0xffff0000, v95
	s_mov_b64 exec, s[28:29]
	v_pk_add_f32 v[160:161], v[144:145], v[152:153] neg_lo:[0,1] neg_hi:[0,1]
	v_pk_add_f32 v[162:163], v[146:147], v[154:155] neg_lo:[0,1] neg_hi:[0,1]
	v_pk_add_f32 v[164:165], v[148:149], v[156:157] neg_lo:[0,1] neg_hi:[0,1]
	v_pk_add_f32 v[166:167], v[150:151], v[158:159] neg_lo:[0,1] neg_hi:[0,1]
	s_mov_b64 exec, -1
	v_lshlrev_b32_e32 v152, 16, v84
	v_and_b32_e32 v153, 0xffff0000, v84
	v_lshlrev_b32_e32 v154, 16, v85
	v_and_b32_e32 v155, 0xffff0000, v85
	v_lshlrev_b32_e32 v156, 16, v86
	v_and_b32_e32 v157, 0xffff0000, v86
	v_lshlrev_b32_e32 v158, 16, v87
	v_and_b32_e32 v159, 0xffff0000, v87
	s_mov_b64 exec, s[30:31]
	v_pk_add_f32 v[160:161], v[144:145], v[152:153] neg_lo:[0,1] neg_hi:[0,1]
	v_pk_add_f32 v[162:163], v[146:147], v[154:155] neg_lo:[0,1] neg_hi:[0,1]
	v_pk_add_f32 v[164:165], v[148:149], v[156:157] neg_lo:[0,1] neg_hi:[0,1]
	v_pk_add_f32 v[166:167], v[150:151], v[158:159] neg_lo:[0,1] neg_hi:[0,1]
	s_mov_b64 exec, -1
	v_pk_add_f32 v[8:9], v[8:9], v[160:161]
	v_pk_add_f32 v[10:11], v[10:11], v[162:163]
	v_pk_add_f32 v[12:13], v[12:13], v[164:165]
	v_pk_add_f32 v[14:15], v[14:15], v[166:167]
	v_pk_fma_f32 v[168:169], v[8:9], v[4:5], v[144:145] neg_lo:[0,0,1] neg_hi:[0,0,1]
	v_pk_fma_f32 v[170:171], v[10:11], v[4:5], v[146:147] neg_lo:[0,0,1] neg_hi:[0,0,1]
	v_pk_fma_f32 v[172:173], v[12:13], v[4:5], v[148:149] neg_lo:[0,0,1] neg_hi:[0,0,1]
	v_pk_fma_f32 v[174:175], v[14:15], v[4:5], v[150:151] neg_lo:[0,0,1] neg_hi:[0,0,1]
	v_cvt_pk_bf16_f32 v176, v168, v169
	v_cvt_pk_bf16_f32 v177, v170, v171
	v_cvt_pk_bf16_f32 v178, v172, v173
	v_cvt_pk_bf16_f32 v179, v174, v175
	s_nop 0
	global_store_dwordx4 v3, v[176:179], s[26:27] offset:2048
	s_nop 1
	s_waitcnt vmcnt(15)
	v_lshlrev_b32_e32 v144, 16, v104
	v_and_b32_e32 v145, 0xffff0000, v104
	v_lshlrev_b32_e32 v146, 16, v105
	v_and_b32_e32 v147, 0xffff0000, v105
	v_lshlrev_b32_e32 v148, 16, v106
	v_and_b32_e32 v149, 0xffff0000, v106
	v_lshlrev_b32_e32 v150, 16, v107
	v_and_b32_e32 v151, 0xffff0000, v107
	v_lshlrev_b32_e32 v152, 16, v96
	v_and_b32_e32 v153, 0xffff0000, v96
	v_lshlrev_b32_e32 v154, 16, v97
	v_and_b32_e32 v155, 0xffff0000, v97
	v_lshlrev_b32_e32 v156, 16, v98
	v_and_b32_e32 v157, 0xffff0000, v98
	v_lshlrev_b32_e32 v158, 16, v99
	v_and_b32_e32 v159, 0xffff0000, v99
	s_mov_b64 exec, s[28:29]
	v_pk_add_f32 v[160:161], v[144:145], v[152:153] neg_lo:[0,1] neg_hi:[0,1]
	v_pk_add_f32 v[162:163], v[146:147], v[154:155] neg_lo:[0,1] neg_hi:[0,1]
	v_pk_add_f32 v[164:165], v[148:149], v[156:157] neg_lo:[0,1] neg_hi:[0,1]
	v_pk_add_f32 v[166:167], v[150:151], v[158:159] neg_lo:[0,1] neg_hi:[0,1]
	s_mov_b64 exec, -1
	v_lshlrev_b32_e32 v152, 16, v88
	v_and_b32_e32 v153, 0xffff0000, v88
	v_lshlrev_b32_e32 v154, 16, v89
	v_and_b32_e32 v155, 0xffff0000, v89
	v_lshlrev_b32_e32 v156, 16, v90
	v_and_b32_e32 v157, 0xffff0000, v90
	v_lshlrev_b32_e32 v158, 16, v91
	v_and_b32_e32 v159, 0xffff0000, v91
	s_mov_b64 exec, s[30:31]
	v_pk_add_f32 v[160:161], v[144:145], v[152:153] neg_lo:[0,1] neg_hi:[0,1]
	v_pk_add_f32 v[162:163], v[146:147], v[154:155] neg_lo:[0,1] neg_hi:[0,1]
	v_pk_add_f32 v[164:165], v[148:149], v[156:157] neg_lo:[0,1] neg_hi:[0,1]
	v_pk_add_f32 v[166:167], v[150:151], v[158:159] neg_lo:[0,1] neg_hi:[0,1]
	s_mov_b64 exec, -1
	v_pk_add_f32 v[8:9], v[8:9], v[160:161]
	v_pk_add_f32 v[10:11], v[10:11], v[162:163]
	v_pk_add_f32 v[12:13], v[12:13], v[164:165]
	v_pk_add_f32 v[14:15], v[14:15], v[166:167]
	v_pk_fma_f32 v[168:169], v[8:9], v[4:5], v[144:145] neg_lo:[0,0,1] neg_hi:[0,0,1]
	v_pk_fma_f32 v[170:171], v[10:11], v[4:5], v[146:147] neg_lo:[0,0,1] neg_hi:[0,0,1]
	v_pk_fma_f32 v[172:173], v[12:13], v[4:5], v[148:149] neg_lo:[0,0,1] neg_hi:[0,0,1]
	v_pk_fma_f32 v[174:175], v[14:15], v[4:5], v[150:151] neg_lo:[0,0,1] neg_hi:[0,0,1]
	v_cvt_pk_bf16_f32 v176, v168, v169
	v_cvt_pk_bf16_f32 v177, v170, v171
	v_cvt_pk_bf16_f32 v178, v172, v173
	v_cvt_pk_bf16_f32 v179, v174, v175
	s_add_u32 s26, s22, 0x3000
	s_addc_u32 s27, s23, 0
	s_nop 0
	global_store_dwordx4 v3, v[176:179], s[26:27]
	s_nop 1
	s_waitcnt vmcnt(15)
; #define GAS __attribute__((address_space(1)))
; __device__ __forceinline__ unsigned pk2(float lo, float hi) { return f2bf(lo) | (f2bf(hi) << 16); }
; #define WSB(F, off) ((bf16*)(wsq((F).ws) + (off)))
; __device__ __forceinline__ void pool_unit(const Frame& F, int layer, int uid) {
;     ...
;     for (int tt = 0; tt < 16; ++tt) {
;         const int t = ts + tt;
;         float vn[8], vo[8]; pool_row(F, layer, stream, b, rowbase, t, ch, vn);
;         if (tt > 0) pool_row(F, layer, stream, b, rowbase, t - win, ch, vo);
; #pragma unroll
;         for (int e = 0; e < 8; ++e) acc[e] += vn[e] - (tt > 0 ? vo[e] : 0.f);
;         const int have = (stream == 2) ? (t + 1 < win ? t + 1 : win) : win;
;         const float inv = 1.0f / (float)have;
;         float y[8];
; #pragma unroll
;         for (int e = 0; e < 8; ++e) y[e] = acc[e] * inv - vn[e];
;         *(GAS v4u*)(WSB(F, WS_BR) + (size_t)2 * M_PAD * D + (size_t)(rowbase + t) * D + ch * 8) = (v4u){pk2(y[0], y[1]), pk2(y[2], y[3]), pk2(y[4], y[5]), pk2(y[6], y[7])};
	v_lshlrev_b32_e32 v144, 16, v108
	v_and_b32_e32 v145, 0xffff0000, v108
	v_lshlrev_b32_e32 v146, 16, v109
	v_and_b32_e32 v147, 0xffff0000, v109
	v_lshlrev_b32_e32 v148, 16, v110
	v_and_b32_e32 v149, 0xffff0000, v110
	v_lshlrev_b32_e32 v150, 16, v111
	v_and_b32_e32 v151, 0xffff0000, v111
	v_lshlrev_b32_e32 v152, 16, v100
	v_and_b32_e32 v153, 0xffff0000, v100
	v_lshlrev_b32_e32 v154, 16, v101
	v_and_b32_e32 v155, 0xffff0000, v101
	v_lshlrev_b32_e32 v156, 16, v102
	v_and_b32_e32 v157, 0xffff0000, v102
	v_lshlrev_b32_e32 v158, 16, v103
	v_and_b32_e32 v159, 0xffff0000, v103
	s_mov_b64 exec, s[28:29]
	v_pk_add_f32 v[160:161], v[144:145], v[152:153] neg_lo:[0,1] neg_hi:[0,1]
	v_pk_add_f32 v[162:163], v[146:147], v[154:155] neg_lo:[0,1] neg_hi:[0,1]
	v_pk_add_f32 v[164:165], v[148:149], v[156:157] neg_lo:[0,1] neg_hi:[0,1]
	v_pk_add_f32 v[166:167], v[150:151], v[158:159] neg_lo:[0,1] neg_hi:[0,1]
	s_mov_b64 exec, -1
	v_lshlrev_b32_e32 v152, 16, v92
	v_and_b32_e32 v153, 0xffff0000, v92
	v_lshlrev_b32_e32 v154, 16, v93
	v_and_b32_e32 v155, 0xffff0000, v93
	v_lshlrev_b32_e32 v156, 16, v94
	v_and_b32_e32 v157, 0xffff0000, v94
	v_lshlrev_b32_e32 v158, 16, v95
	v_and_b32_e32 v159, 0xffff0000, v95
	s_mov_b64 exec, s[30:31]
	v_pk_add_f32 v[160:161], v[144:145], v[152:153] neg_lo:[0,1] neg_hi:[0,1]
	v_pk_add_f32 v[162:163], v[146:147], v[154:155] neg_lo:[0,1] neg_hi:[0,1]
	v_pk_add_f32 v[164:165], v[148:149], v[156:157] neg_lo:[0,1] neg_hi:[0,1]
	v_pk_add_f32 v[166:167], v[150:151], v[158:159] neg_lo:[0,1] neg_hi:[0,1]
	s_mov_b64 exec, -1
	v_pk_add_f32 v[8:9], v[8:9], v[160:161]
	v_pk_add_f32 v[10:11], v[10:11], v[162:163]
	v_pk_add_f32 v[12:13], v[12:13], v[164:165]
	v_pk_add_f32 v[14:15], v[14:15], v[166:167]
	v_pk_fma_f32 v[168:169], v[8:9], v[4:5], v[144:145] neg_lo:[0,0,1] neg_hi:[0,0,1]
	v_pk_fma_f32 v[170:171], v[10:11], v[4:5], v[146:147] neg_lo:[0,0,1] neg_hi:[0,0,1]
	v_pk_fma_f32 v[172:173], v[12:13], v[4:5], v[148:149] neg_lo:[0,0,1] neg_hi:[0,0,1]
	v_pk_fma_f32 v[174:175], v[14:15], v[4:5], v[150:151] neg_lo:[0,0,1] neg_hi:[0,0,1]
	v_cvt_pk_bf16_f32 v176, v168, v169
	v_cvt_pk_bf16_f32 v177, v170, v171
	v_cvt_pk_bf16_f32 v178, v172, v173
	v_cvt_pk_bf16_f32 v179, v174, v175
	s_nop 0
	global_store_dwordx4 v3, v[176:179], s[26:27] offset:2048
	s_nop 1
	s_waitcnt vmcnt(15)
	v_lshlrev_b32_e32 v144, 16, v112
	v_and_b32_e32 v145, 0xffff0000, v112
	v_lshlrev_b32_e32 v146, 16, v113
	v_and_b32_e32 v147, 0xffff0000, v113
	v_lshlrev_b32_e32 v148, 16, v114
	v_and_b32_e32 v149, 0xffff0000, v114
	v_lshlrev_b32_e32 v150, 16, v115
	v_and_b32_e32 v151, 0xffff0000, v115
	v_lshlrev_b32_e32 v152, 16, v104
	v_and_b32_e32 v153, 0xffff0000, v104
	v_lshlrev_b32_e32 v154, 16, v105
	v_and_b32_e32 v155, 0xffff0000, v105
	v_lshlrev_b32_e32 v156, 16, v106
	v_and_b32_e32 v157, 0xffff0000, v106
	v_lshlrev_b32_e32 v158, 16, v107
	v_and_b32_e32 v159, 0xffff0000, v107
	s_mov_b64 exec, s[28:29]
	v_pk_add_f32 v[160:161], v[144:145], v[152:153] neg_lo:[0,1] neg_hi:[0,1]
	v_pk_add_f32 v[162:163], v[146:147], v[154:155] neg_lo:[0,1] neg_hi:[0,1]
	v_pk_add_f32 v[164:165], v[148:149], v[156:157] neg_lo:[0,1] neg_hi:[0,1]
	v_pk_add_f32 v[166:167], v[150:151], v[158:159] neg_lo:[0,1] neg_hi:[0,1]
	s_mov_b64 exec, -1
	v_lshlrev_b32_e32 v152, 16, v96
	v_and_b32_e32 v153, 0xffff0000, v96
	v_lshlrev_b32_e32 v154, 16, v97
	v_and_b32_e32 v155, 0xffff0000, v97
	v_lshlrev_b32_e32 v156, 16, v98
	v_and_b32_e32 v157, 0xffff0000, v98
	v_lshlrev_b32_e32 v158, 16, v99
	v_and_b32_e32 v159, 0xffff0000, v99
	s_mov_b64 exec, s[30:31]
	v_pk_add_f32 v[160:161], v[144:145], v[152:153] neg_lo:[0,1] neg_hi:[0,1]
	v_pk_add_f32 v[162:163], v[146:147], v[154:155] neg_lo:[0,1] neg_hi:[0,1]
	v_pk_add_f32 v[164:165], v[148:149], v[156:157] neg_lo:[0,1] neg_hi:[0,1]
	v_pk_add_f32 v[166:167], v[150:151], v[158:159] neg_lo:[0,1] neg_hi:[0,1]
	s_mov_b64 exec, -1
	v_pk_add_f32 v[8:9], v[8:9], v[160:161]
	v_pk_add_f32 v[10:11], v[10:11], v[162:163]
	v_pk_add_f32 v[12:13], v[12:13], v[164:165]
	v_pk_add_f32 v[14:15], v[14:15], v[166:167]
	v_pk_fma_f32 v[168:169], v[8:9], v[4:5], v[144:145] neg_lo:[0,0,1] neg_hi:[0,0,1]
	v_pk_fma_f32 v[170:171], v[10:11], v[4:5], v[146:147] neg_lo:[0,0,1] neg_hi:[0,0,1]
	v_pk_fma_f32 v[172:173], v[12:13], v[4:5], v[148:149] neg_lo:[0,0,1] neg_hi:[0,0,1]
	v_pk_fma_f32 v[174:175], v[14:15], v[4:5], v[150:151] neg_lo:[0,0,1] neg_hi:[0,0,1]
	v_cvt_pk_bf16_f32 v176, v168, v169
	v_cvt_pk_bf16_f32 v177, v170, v171
	v_cvt_pk_bf16_f32 v178, v172, v173
	v_cvt_pk_bf16_f32 v179, v174, v175
	s_add_u32 s26, s22, 0x4000
	s_addc_u32 s27, s23, 0
	s_nop 0
	global_store_dwordx4 v3, v[176:179], s[26:27]
	s_nop 1
	s_waitcnt vmcnt(15)
; #define GAS __attribute__((address_space(1)))
; __device__ __forceinline__ unsigned pk2(float lo, float hi) { return f2bf(lo) | (f2bf(hi) << 16); }
; #define WSB(F, off) ((bf16*)(wsq((F).ws) + (off)))
; __device__ __forceinline__ void pool_unit(const Frame& F, int layer, int uid) {
;     ...
;     for (int tt = 0; tt < 16; ++tt) {
;         const int t = ts + tt;
;         float vn[8], vo[8]; pool_row(F, layer, stream, b, rowbase, t, ch, vn);
;         if (tt > 0) pool_row(F, layer, stream, b, rowbase, t - win, ch, vo);
; #pragma unroll
;         for (int e = 0; e < 8; ++e) acc[e] += vn[e] - (tt > 0 ? vo[e] : 0.f);
;         const int have = (stream == 2) ? (t + 1 < win ? t + 1 : win) : win;
;         const float inv = 1.0f / (float)have;
;         float y[8];
; #pragma unroll
;         for (int e = 0; e < 8; ++e) y[e] = acc[e] * inv - vn[e];
;         *(GAS v4u*)(WSB(F, WS_BR) + (size_t)2 * M_PAD * D + (size_t)(rowbase + t) * D + ch * 8) = (v4u){pk2(y[0], y[1]), pk2(y[2], y[3]), pk2(y[4], y[5]), pk2(y[6], y[7])};
	v_lshlrev_b32_e32 v144, 16, v116
	v_and_b32_e32 v145, 0xffff0000, v116
	v_lshlrev_b32_e32 v146, 16, v117
	v_and_b32_e32 v147, 0xffff0000, v117
	v_lshlrev_b32_e32 v148, 16, v118
	v_and_b32_e32 v149, 0xffff0000, v118
	v_lshlrev_b32_e32 v150, 16, v119
	v_and_b32_e32 v151, 0xffff0000, v119
	v_lshlrev_b32_e32 v152, 16, v108
	v_and_b32_e32 v153, 0xffff0000, v108
	v_lshlrev_b32_e32 v154, 16, v109
	v_and_b32_e32 v155, 0xffff0000, v109
	v_lshlrev_b32_e32 v156, 16, v110
	v_and_b32_e32 v157, 0xffff0000, v110
	v_lshlrev_b32_e32 v158, 16, v111
	v_and_b32_e32 v159, 0xffff0000, v111
	s_mov_b64 exec, s[28:29]
	v_pk_add_f32 v[160:161], v[144:145], v[152:153] neg_lo:[0,1] neg_hi:[0,1]
	v_pk_add_f32 v[162:163], v[146:147], v[154:155] neg_lo:[0,1] neg_hi:[0,1]
	v_pk_add_f32 v[164:165], v[148:149], v[156:157] neg_lo:[0,1] neg_hi:[0,1]
	v_pk_add_f32 v[166:167], v[150:151], v[158:159] neg_lo:[0,1] neg_hi:[0,1]
	s_mov_b64 exec, -1
	v_lshlrev_b32_e32 v152, 16, v100
	v_and_b32_e32 v153, 0xffff0000, v100
	v_lshlrev_b32_e32 v154, 16, v101
	v_and_b32_e32 v155, 0xffff0000, v101
	v_lshlrev_b32_e32 v156, 16, v102
	v_and_b32_e32 v157, 0xffff0000, v102
	v_lshlrev_b32_e32 v158, 16, v103
	v_and_b32_e32 v159, 0xffff0000, v103
	s_mov_b64 exec, s[30:31]
	v_pk_add_f32 v[160:161], v[144:145], v[152:153] neg_lo:[0,1] neg_hi:[0,1]
	v_pk_add_f32 v[162:163], v[146:147], v[154:155] neg_lo:[0,1] neg_hi:[0,1]
	v_pk_add_f32 v[164:165], v[148:149], v[156:157] neg_lo:[0,1] neg_hi:[0,1]
	v_pk_add_f32 v[166:167], v[150:151], v[158:159] neg_lo:[0,1] neg_hi:[0,1]
	s_mov_b64 exec, -1
	v_pk_add_f32 v[8:9], v[8:9], v[160:161]
	v_pk_add_f32 v[10:11], v[10:11], v[162:163]
	v_pk_add_f32 v[12:13], v[12:13], v[164:165]
	v_pk_add_f32 v[14:15], v[14:15], v[166:167]
	v_pk_fma_f32 v[168:169], v[8:9], v[4:5], v[144:145] neg_lo:[0,0,1] neg_hi:[0,0,1]
	v_pk_fma_f32 v[170:171], v[10:11], v[4:5], v[146:147] neg_lo:[0,0,1] neg_hi:[0,0,1]
	v_pk_fma_f32 v[172:173], v[12:13], v[4:5], v[148:149] neg_lo:[0,0,1] neg_hi:[0,0,1]
	v_pk_fma_f32 v[174:175], v[14:15], v[4:5], v[150:151] neg_lo:[0,0,1] neg_hi:[0,0,1]
	v_cvt_pk_bf16_f32 v176, v168, v169
	v_cvt_pk_bf16_f32 v177, v170, v171
	v_cvt_pk_bf16_f32 v178, v172, v173
	v_cvt_pk_bf16_f32 v179, v174, v175
	s_nop 0
	global_store_dwordx4 v3, v[176:179], s[26:27] offset:2048
	s_nop 1
	s_waitcnt vmcnt(15)
	v_lshlrev_b32_e32 v144, 16, v120
	v_and_b32_e32 v145, 0xffff0000, v120
	v_lshlrev_b32_e32 v146, 16, v121
	v_and_b32_e32 v147, 0xffff0000, v121
	v_lshlrev_b32_e32 v148, 16, v122
	v_and_b32_e32 v149, 0xffff0000, v122
	v_lshlrev_b32_e32 v150, 16, v123
	v_and_b32_e32 v151, 0xffff0000, v123
	v_lshlrev_b32_e32 v152, 16, v112
	v_and_b32_e32 v153, 0xffff0000, v112
	v_lshlrev_b32_e32 v154, 16, v113
	v_and_b32_e32 v155, 0xffff0000, v113
	v_lshlrev_b32_e32 v156, 16, v114
	v_and_b32_e32 v157, 0xffff0000, v114
	v_lshlrev_b32_e32 v158, 16, v115
	v_and_b32_e32 v159, 0xffff0000, v115
	s_mov_b64 exec, s[28:29]
	v_pk_add_f32 v[160:161], v[144:145], v[152:153] neg_lo:[0,1] neg_hi:[0,1]
	v_pk_add_f32 v[162:163], v[146:147], v[154:155] neg_lo:[0,1] neg_hi:[0,1]
	v_pk_add_f32 v[164:165], v[148:149], v[156:157] neg_lo:[0,1] neg_hi:[0,1]
	v_pk_add_f32 v[166:167], v[150:151], v[158:159] neg_lo:[0,1] neg_hi:[0,1]
	s_mov_b64 exec, -1
	v_lshlrev_b32_e32 v152, 16, v104
	v_and_b32_e32 v153, 0xffff0000, v104
	v_lshlrev_b32_e32 v154, 16, v105
	v_and_b32_e32 v155, 0xffff0000, v105
	v_lshlrev_b32_e32 v156, 16, v106
	v_and_b32_e32 v157, 0xffff0000, v106
	v_lshlrev_b32_e32 v158, 16, v107
	v_and_b32_e32 v159, 0xffff0000, v107
	s_mov_b64 exec, s[30:31]
	v_pk_add_f32 v[160:161], v[144:145], v[152:153] neg_lo:[0,1] neg_hi:[0,1]
	v_pk_add_f32 v[162:163], v[146:147], v[154:155] neg_lo:[0,1] neg_hi:[0,1]
	v_pk_add_f32 v[164:165], v[148:149], v[156:157] neg_lo:[0,1] neg_hi:[0,1]
	v_pk_add_f32 v[166:167], v[150:151], v[158:159] neg_lo:[0,1] neg_hi:[0,1]
	s_mov_b64 exec, -1
	v_pk_add_f32 v[8:9], v[8:9], v[160:161]
	v_pk_add_f32 v[10:11], v[10:11], v[162:163]
	v_pk_add_f32 v[12:13], v[12:13], v[164:165]
	v_pk_add_f32 v[14:15], v[14:15], v[166:167]
	v_pk_fma_f32 v[168:169], v[8:9], v[4:5], v[144:145] neg_lo:[0,0,1] neg_hi:[0,0,1]
	v_pk_fma_f32 v[170:171], v[10:11], v[4:5], v[146:147] neg_lo:[0,0,1] neg_hi:[0,0,1]
	v_pk_fma_f32 v[172:173], v[12:13], v[4:5], v[148:149] neg_lo:[0,0,1] neg_hi:[0,0,1]
	v_pk_fma_f32 v[174:175], v[14:15], v[4:5], v[150:151] neg_lo:[0,0,1] neg_hi:[0,0,1]
	v_cvt_pk_bf16_f32 v176, v168, v169
	v_cvt_pk_bf16_f32 v177, v170, v171
	v_cvt_pk_bf16_f32 v178, v172, v173
	v_cvt_pk_bf16_f32 v179, v174, v175
	s_add_u32 s26, s22, 0x5000
	s_addc_u32 s27, s23, 0
	s_nop 0
	global_store_dwordx4 v3, v[176:179], s[26:27]
	s_nop 1
	s_waitcnt vmcnt(15)
; #define GAS __attribute__((address_space(1)))
; __device__ __forceinline__ unsigned pk2(float lo, float hi) { return f2bf(lo) | (f2bf(hi) << 16); }
; #define WSB(F, off) ((bf16*)(wsq((F).ws) + (off)))
; __device__ __forceinline__ void pool_unit(const Frame& F, int layer, int uid) {
;     ...
;     for (int tt = 0; tt < 16; ++tt) {
;         const int t = ts + tt;
;         float vn[8], vo[8]; pool_row(F, layer, stream, b, rowbase, t, ch, vn);
;         if (tt > 0) pool_row(F, layer, stream, b, rowbase, t - win, ch, vo);
; #pragma unroll
;         for (int e = 0; e < 8; ++e) acc[e] += vn[e] - (tt > 0 ? vo[e] : 0.f);
;         const int have = (stream == 2) ? (t + 1 < win ? t + 1 : win) : win;
;         const float inv = 1.0f / (float)have;
;         float y[8];
; #pragma unroll
;         for (int e = 0; e < 8; ++e) y[e] = acc[e] * inv - vn[e];
;         *(GAS v4u*)(WSB(F, WS_BR) + (size_t)2 * M_PAD * D + (size_t)(rowbase + t) * D + ch * 8) = (v4u){pk2(y[0], y[1]), pk2(y[2], y[3]), pk2(y[4], y[5]), pk2(y[6], y[7])};
	v_lshlrev_b32_e32 v144, 16, v124
	v_and_b32_e32 v145, 0xffff0000, v124
	v_lshlrev_b32_e32 v146, 16, v125
	v_and_b32_e32 v147, 0xffff0000, v125
	v_lshlrev_b32_e32 v148, 16, v126
	v_and_b32_e32 v149, 0xffff0000, v126
	v_lshlrev_b32_e32 v150, 16, v127
	v_and_b32_e32 v151, 0xffff0000, v127
	v_lshlrev_b32_e32 v152, 16, v116
	v_and_b32_e32 v153, 0xffff0000, v116
	v_lshlrev_b32_e32 v154, 16, v117
	v_and_b32_e32 v155, 0xffff0000, v117
	v_lshlrev_b32_e32 v156, 16, v118
	v_and_b32_e32 v157, 0xffff0000, v118
	v_lshlrev_b32_e32 v158, 16, v119
	v_and_b32_e32 v159, 0xffff0000, v119
	s_mov_b64 exec, s[28:29]
	v_pk_add_f32 v[160:161], v[144:145], v[152:153] neg_lo:[0,1] neg_hi:[0,1]
	v_pk_add_f32 v[162:163], v[146:147], v[154:155] neg_lo:[0,1] neg_hi:[0,1]
	v_pk_add_f32 v[164:165], v[148:149], v[156:157] neg_lo:[0,1] neg_hi:[0,1]
	v_pk_add_f32 v[166:167], v[150:151], v[158:159] neg_lo:[0,1] neg_hi:[0,1]
	s_mov_b64 exec, -1
	v_lshlrev_b32_e32 v152, 16, v108
	v_and_b32_e32 v153, 0xffff0000, v108
	v_lshlrev_b32_e32 v154, 16, v109
	v_and_b32_e32 v155, 0xffff0000, v109
	v_lshlrev_b32_e32 v156, 16, v110
	v_and_b32_e32 v157, 0xffff0000, v110
	v_lshlrev_b32_e32 v158, 16, v111
	v_and_b32_e32 v159, 0xffff0000, v111
	s_mov_b64 exec, s[30:31]
	v_pk_add_f32 v[160:161], v[144:145], v[152:153] neg_lo:[0,1] neg_hi:[0,1]
	v_pk_add_f32 v[162:163], v[146:147], v[154:155] neg_lo:[0,1] neg_hi:[0,1]
	v_pk_add_f32 v[164:165], v[148:149], v[156:157] neg_lo:[0,1] neg_hi:[0,1]
	v_pk_add_f32 v[166:167], v[150:151], v[158:159] neg_lo:[0,1] neg_hi:[0,1]
	s_mov_b64 exec, -1
	v_pk_add_f32 v[8:9], v[8:9], v[160:161]
	v_pk_add_f32 v[10:11], v[10:11], v[162:163]
	v_pk_add_f32 v[12:13], v[12:13], v[164:165]
	v_pk_add_f32 v[14:15], v[14:15], v[166:167]
	v_pk_fma_f32 v[168:169], v[8:9], v[4:5], v[144:145] neg_lo:[0,0,1] neg_hi:[0,0,1]
	v_pk_fma_f32 v[170:171], v[10:11], v[4:5], v[146:147] neg_lo:[0,0,1] neg_hi:[0,0,1]
	v_pk_fma_f32 v[172:173], v[12:13], v[4:5], v[148:149] neg_lo:[0,0,1] neg_hi:[0,0,1]
	v_pk_fma_f32 v[174:175], v[14:15], v[4:5], v[150:151] neg_lo:[0,0,1] neg_hi:[0,0,1]
	v_cvt_pk_bf16_f32 v176, v168, v169
	v_cvt_pk_bf16_f32 v177, v170, v171
	v_cvt_pk_bf16_f32 v178, v172, v173
	v_cvt_pk_bf16_f32 v179, v174, v175
	s_nop 0
	global_store_dwordx4 v3, v[176:179], s[26:27] offset:2048
	s_nop 1
	s_waitcnt vmcnt(15)
	v_lshlrev_b32_e32 v144, 16, v128
	v_and_b32_e32 v145, 0xffff0000, v128
	v_lshlrev_b32_e32 v146, 16, v129
	v_and_b32_e32 v147, 0xffff0000, v129
	v_lshlrev_b32_e32 v148, 16, v130
	v_and_b32_e32 v149, 0xffff0000, v130
	v_lshlrev_b32_e32 v150, 16, v131
	v_and_b32_e32 v151, 0xffff0000, v131
	v_lshlrev_b32_e32 v152, 16, v120
	v_and_b32_e32 v153, 0xffff0000, v120
	v_lshlrev_b32_e32 v154, 16, v121
	v_and_b32_e32 v155, 0xffff0000, v121
	v_lshlrev_b32_e32 v156, 16, v122
	v_and_b32_e32 v157, 0xffff0000, v122
	v_lshlrev_b32_e32 v158, 16, v123
	v_and_b32_e32 v159, 0xffff0000, v123
	s_mov_b64 exec, s[28:29]
	v_pk_add_f32 v[160:161], v[144:145], v[152:153] neg_lo:[0,1] neg_hi:[0,1]
	v_pk_add_f32 v[162:163], v[146:147], v[154:155] neg_lo:[0,1] neg_hi:[0,1]
	v_pk_add_f32 v[164:165], v[148:149], v[156:157] neg_lo:[0,1] neg_hi:[0,1]
	v_pk_add_f32 v[166:167], v[150:151], v[158:159] neg_lo:[0,1] neg_hi:[0,1]
	s_mov_b64 exec, -1
	v_lshlrev_b32_e32 v152, 16, v112
	v_and_b32_e32 v153, 0xffff0000, v112
	v_lshlrev_b32_e32 v154, 16, v113
	v_and_b32_e32 v155, 0xffff0000, v113
	v_lshlrev_b32_e32 v156, 16, v114
	v_and_b32_e32 v157, 0xffff0000, v114
	v_lshlrev_b32_e32 v158, 16, v115
	v_and_b32_e32 v159, 0xffff0000, v115
	s_mov_b64 exec, s[30:31]
	v_pk_add_f32 v[160:161], v[144:145], v[152:153] neg_lo:[0,1] neg_hi:[0,1]
	v_pk_add_f32 v[162:163], v[146:147], v[154:155] neg_lo:[0,1] neg_hi:[0,1]
	v_pk_add_f32 v[164:165], v[148:149], v[156:157] neg_lo:[0,1] neg_hi:[0,1]
	v_pk_add_f32 v[166:167], v[150:151], v[158:159] neg_lo:[0,1] neg_hi:[0,1]
	s_mov_b64 exec, -1
	v_pk_add_f32 v[8:9], v[8:9], v[160:161]
	v_pk_add_f32 v[10:11], v[10:11], v[162:163]
	v_pk_add_f32 v[12:13], v[12:13], v[164:165]
	v_pk_add_f32 v[14:15], v[14:15], v[166:167]
	v_pk_fma_f32 v[168:169], v[8:9], v[4:5], v[144:145] neg_lo:[0,0,1] neg_hi:[0,0,1]
	v_pk_fma_f32 v[170:171], v[10:11], v[4:5], v[146:147] neg_lo:[0,0,1] neg_hi:[0,0,1]
	v_pk_fma_f32 v[172:173], v[12:13], v[4:5], v[148:149] neg_lo:[0,0,1] neg_hi:[0,0,1]
	v_pk_fma_f32 v[174:175], v[14:15], v[4:5], v[150:151] neg_lo:[0,0,1] neg_hi:[0,0,1]
	v_cvt_pk_bf16_f32 v176, v168, v169
	v_cvt_pk_bf16_f32 v177, v170, v171
	v_cvt_pk_bf16_f32 v178, v172, v173
	v_cvt_pk_bf16_f32 v179, v174, v175
	s_add_u32 s26, s22, 0x6000
	s_addc_u32 s27, s23, 0
	s_nop 0
	global_store_dwordx4 v3, v[176:179], s[26:27]
	s_nop 1
	s_waitcnt vmcnt(15)
; #define GAS __attribute__((address_space(1)))
; __device__ __forceinline__ unsigned pk2(float lo, float hi) { return f2bf(lo) | (f2bf(hi) << 16); }
; #define WSB(F, off) ((bf16*)(wsq((F).ws) + (off)))
; __device__ __forceinline__ void pool_unit(const Frame& F, int layer, int uid) {
;     ...
;     for (int tt = 0; tt < 16; ++tt) {
;         const int t = ts + tt;
;         float vn[8], vo[8]; pool_row(F, layer, stream, b, rowbase, t, ch, vn);
;         if (tt > 0) pool_row(F, layer, stream, b, rowbase, t - win, ch, vo);
; #pragma unroll
;         for (int e = 0; e < 8; ++e) acc[e] += vn[e] - (tt > 0 ? vo[e] : 0.f);
;         const int have = (stream == 2) ? (t + 1 < win ? t + 1 : win) : win;
;         const float inv = 1.0f / (float)have;
;         float y[8];
; #pragma unroll
;         for (int e = 0; e < 8; ++e) y[e] = acc[e] * inv - vn[e];
;         *(GAS v4u*)(WSB(F, WS_BR) + (size_t)2 * M_PAD * D + (size_t)(rowbase + t) * D + ch * 8) = (v4u){pk2(y[0], y[1]), pk2(y[2], y[3]), pk2(y[4], y[5]), pk2(y[6], y[7])};
	v_lshlrev_b32_e32 v144, 16, v132
	v_and_b32_e32 v145, 0xffff0000, v132
	v_lshlrev_b32_e32 v146, 16, v133
	v_and_b32_e32 v147, 0xffff0000, v133
	v_lshlrev_b32_e32 v148, 16, v134
	v_and_b32_e32 v149, 0xffff0000, v134
	v_lshlrev_b32_e32 v150, 16, v135
	v_and_b32_e32 v151, 0xffff0000, v135
	v_lshlrev_b32_e32 v152, 16, v124
	v_and_b32_e32 v153, 0xffff0000, v124
	v_lshlrev_b32_e32 v154, 16, v125
	v_and_b32_e32 v155, 0xffff0000, v125
	v_lshlrev_b32_e32 v156, 16, v126
	v_and_b32_e32 v157, 0xffff0000, v126
	v_lshlrev_b32_e32 v158, 16, v127
	v_and_b32_e32 v159, 0xffff0000, v127
	s_mov_b64 exec, s[28:29]
	v_pk_add_f32 v[160:161], v[144:145], v[152:153] neg_lo:[0,1] neg_hi:[0,1]
	v_pk_add_f32 v[162:163], v[146:147], v[154:155] neg_lo:[0,1] neg_hi:[0,1]
	v_pk_add_f32 v[164:165], v[148:149], v[156:157] neg_lo:[0,1] neg_hi:[0,1]
	v_pk_add_f32 v[166:167], v[150:151], v[158:159] neg_lo:[0,1] neg_hi:[0,1]
	s_mov_b64 exec, -1
	v_lshlrev_b32_e32 v152, 16, v116
	v_and_b32_e32 v153, 0xffff0000, v116
	v_lshlrev_b32_e32 v154, 16, v117
	v_and_b32_e32 v155, 0xffff0000, v117
	v_lshlrev_b32_e32 v156, 16, v118
	v_and_b32_e32 v157, 0xffff0000, v118
	v_lshlrev_b32_e32 v158, 16, v119
	v_and_b32_e32 v159, 0xffff0000, v119
	s_mov_b64 exec, s[30:31]
	v_pk_add_f32 v[160:161], v[144:145], v[152:153] neg_lo:[0,1] neg_hi:[0,1]
	v_pk_add_f32 v[162:163], v[146:147], v[154:155] neg_lo:[0,1] neg_hi:[0,1]
	v_pk_add_f32 v[164:165], v[148:149], v[156:157] neg_lo:[0,1] neg_hi:[0,1]
	v_pk_add_f32 v[166:167], v[150:151], v[158:159] neg_lo:[0,1] neg_hi:[0,1]
	s_mov_b64 exec, -1
	v_pk_add_f32 v[8:9], v[8:9], v[160:161]
	v_pk_add_f32 v[10:11], v[10:11], v[162:163]
	v_pk_add_f32 v[12:13], v[12:13], v[164:165]
	v_pk_add_f32 v[14:15], v[14:15], v[166:167]
	v_pk_fma_f32 v[168:169], v[8:9], v[4:5], v[144:145] neg_lo:[0,0,1] neg_hi:[0,0,1]
	v_pk_fma_f32 v[170:171], v[10:11], v[4:5], v[146:147] neg_lo:[0,0,1] neg_hi:[0,0,1]
	v_pk_fma_f32 v[172:173], v[12:13], v[4:5], v[148:149] neg_lo:[0,0,1] neg_hi:[0,0,1]
	v_pk_fma_f32 v[174:175], v[14:15], v[4:5], v[150:151] neg_lo:[0,0,1] neg_hi:[0,0,1]
	v_cvt_pk_bf16_f32 v176, v168, v169
	v_cvt_pk_bf16_f32 v177, v170, v171
	v_cvt_pk_bf16_f32 v178, v172, v173
	v_cvt_pk_bf16_f32 v179, v174, v175
	s_nop 0
	global_store_dwordx4 v3, v[176:179], s[26:27] offset:2048
	s_nop 1
	s_waitcnt vmcnt(15)
	v_lshlrev_b32_e32 v144, 16, v136
	v_and_b32_e32 v145, 0xffff0000, v136
	v_lshlrev_b32_e32 v146, 16, v137
	v_and_b32_e32 v147, 0xffff0000, v137
	v_lshlrev_b32_e32 v148, 16, v138
	v_and_b32_e32 v149, 0xffff0000, v138
	v_lshlrev_b32_e32 v150, 16, v139
	v_and_b32_e32 v151, 0xffff0000, v139
	v_lshlrev_b32_e32 v152, 16, v128
	v_and_b32_e32 v153, 0xffff0000, v128
	v_lshlrev_b32_e32 v154, 16, v129
	v_and_b32_e32 v155, 0xffff0000, v129
	v_lshlrev_b32_e32 v156, 16, v130
	v_and_b32_e32 v157, 0xffff0000, v130
	v_lshlrev_b32_e32 v158, 16, v131
	v_and_b32_e32 v159, 0xffff0000, v131
	s_mov_b64 exec, s[28:29]
	v_pk_add_f32 v[160:161], v[144:145], v[152:153] neg_lo:[0,1] neg_hi:[0,1]
	v_pk_add_f32 v[162:163], v[146:147], v[154:155] neg_lo:[0,1] neg_hi:[0,1]
	v_pk_add_f32 v[164:165], v[148:149], v[156:157] neg_lo:[0,1] neg_hi:[0,1]
	v_pk_add_f32 v[166:167], v[150:151], v[158:159] neg_lo:[0,1] neg_hi:[0,1]
	s_mov_b64 exec, -1
	v_lshlrev_b32_e32 v152, 16, v120
	v_and_b32_e32 v153, 0xffff0000, v120
	v_lshlrev_b32_e32 v154, 16, v121
	v_and_b32_e32 v155, 0xffff0000, v121
	v_lshlrev_b32_e32 v156, 16, v122
	v_and_b32_e32 v157, 0xffff0000, v122
	v_lshlrev_b32_e32 v158, 16, v123
	v_and_b32_e32 v159, 0xffff0000, v123
	s_mov_b64 exec, s[30:31]
	v_pk_add_f32 v[160:161], v[144:145], v[152:153] neg_lo:[0,1] neg_hi:[0,1]
	v_pk_add_f32 v[162:163], v[146:147], v[154:155] neg_lo:[0,1] neg_hi:[0,1]
	v_pk_add_f32 v[164:165], v[148:149], v[156:157] neg_lo:[0,1] neg_hi:[0,1]
	v_pk_add_f32 v[166:167], v[150:151], v[158:159] neg_lo:[0,1] neg_hi:[0,1]
	s_mov_b64 exec, -1
	v_pk_add_f32 v[8:9], v[8:9], v[160:161]
	v_pk_add_f32 v[10:11], v[10:11], v[162:163]
	v_pk_add_f32 v[12:13], v[12:13], v[164:165]
	v_pk_add_f32 v[14:15], v[14:15], v[166:167]
	v_pk_fma_f32 v[168:169], v[8:9], v[4:5], v[144:145] neg_lo:[0,0,1] neg_hi:[0,0,1]
	v_pk_fma_f32 v[170:171], v[10:11], v[4:5], v[146:147] neg_lo:[0,0,1] neg_hi:[0,0,1]
	v_pk_fma_f32 v[172:173], v[12:13], v[4:5], v[148:149] neg_lo:[0,0,1] neg_hi:[0,0,1]
	v_pk_fma_f32 v[174:175], v[14:15], v[4:5], v[150:151] neg_lo:[0,0,1] neg_hi:[0,0,1]
	v_cvt_pk_bf16_f32 v176, v168, v169
	v_cvt_pk_bf16_f32 v177, v170, v171
	v_cvt_pk_bf16_f32 v178, v172, v173
	v_cvt_pk_bf16_f32 v179, v174, v175
	s_add_u32 s26, s22, 0x7000
	s_addc_u32 s27, s23, 0
	s_nop 0
	global_store_dwordx4 v3, v[176:179], s[26:27]
	s_nop 1
	s_waitcnt vmcnt(15)
	v_lshlrev_b32_e32 v144, 16, v140
	v_and_b32_e32 v145, 0xffff0000, v140
	v_lshlrev_b32_e32 v146, 16, v141
	v_and_b32_e32 v147, 0xffff0000, v141
	v_lshlrev_b32_e32 v148, 16, v142
	v_and_b32_e32 v149, 0xffff0000, v142
	v_lshlrev_b32_e32 v150, 16, v143
	v_and_b32_e32 v151, 0xffff0000, v143
	v_lshlrev_b32_e32 v152, 16, v132
	v_and_b32_e32 v153, 0xffff0000, v132
	v_lshlrev_b32_e32 v154, 16, v133
	v_and_b32_e32 v155, 0xffff0000, v133
	v_lshlrev_b32_e32 v156, 16, v134
	v_and_b32_e32 v157, 0xffff0000, v134
	v_lshlrev_b32_e32 v158, 16, v135
	v_and_b32_e32 v159, 0xffff0000, v135
	s_mov_b64 exec, s[28:29]
	v_pk_add_f32 v[160:161], v[144:145], v[152:153] neg_lo:[0,1] neg_hi:[0,1]
	v_pk_add_f32 v[162:163], v[146:147], v[154:155] neg_lo:[0,1] neg_hi:[0,1]
	v_pk_add_f32 v[164:165], v[148:149], v[156:157] neg_lo:[0,1] neg_hi:[0,1]
	v_pk_add_f32 v[166:167], v[150:151], v[158:159] neg_lo:[0,1] neg_hi:[0,1]
	s_mov_b64 exec, -1
	v_lshlrev_b32_e32 v152, 16, v124
	v_and_b32_e32 v153, 0xffff0000, v124
	v_lshlrev_b32_e32 v154, 16, v125
	v_and_b32_e32 v155, 0xffff0000, v125
	v_lshlrev_b32_e32 v156, 16, v126
	v_and_b32_e32 v157, 0xffff0000, v126
	v_lshlrev_b32_e32 v158, 16, v127
	v_and_b32_e32 v159, 0xffff0000, v127
	s_mov_b64 exec, s[30:31]
	v_pk_add_f32 v[160:161], v[144:145], v[152:153] neg_lo:[0,1] neg_hi:[0,1]
	v_pk_add_f32 v[162:163], v[146:147], v[154:155] neg_lo:[0,1] neg_hi:[0,1]
	v_pk_add_f32 v[164:165], v[148:149], v[156:157] neg_lo:[0,1] neg_hi:[0,1]
	v_pk_add_f32 v[166:167], v[150:151], v[158:159] neg_lo:[0,1] neg_hi:[0,1]
	s_mov_b64 exec, -1
	v_pk_add_f32 v[8:9], v[8:9], v[160:161]
	v_pk_add_f32 v[10:11], v[10:11], v[162:163]
	v_pk_add_f32 v[12:13], v[12:13], v[164:165]
	v_pk_add_f32 v[14:15], v[14:15], v[166:167]
	v_pk_fma_f32 v[168:169], v[8:9], v[4:5], v[144:145] neg_lo:[0,0,1] neg_hi:[0,0,1]
	v_pk_fma_f32 v[170:171], v[10:11], v[4:5], v[146:147] neg_lo:[0,0,1] neg_hi:[0,0,1]
	v_pk_fma_f32 v[172:173], v[12:13], v[4:5], v[148:149] neg_lo:[0,0,1] neg_hi:[0,0,1]
	v_pk_fma_f32 v[174:175], v[14:15], v[4:5], v[150:151] neg_lo:[0,0,1] neg_hi:[0,0,1]
	v_cvt_pk_bf16_f32 v176, v168, v169
	v_cvt_pk_bf16_f32 v177, v170, v171
	v_cvt_pk_bf16_f32 v178, v172, v173
	v_cvt_pk_bf16_f32 v179, v174, v175
	s_nop 0
	global_store_dwordx4 v3, v[176:179], s[26:27] offset:2048
	s_nop 1
	s_branch .Lpool_fast_done
; __device__ __forceinline__ TC thread_coords(int wave) { TC c; int l = lane_id_(); asm volatile("" : "+v"(l)); c.lane = l; c.wave = wave; c.tid = wave * 64 + l; return c; }
; __device__ __forceinline__ void pool_unit(const Frame& F, int layer, int uid) {
;     ...
;     const TC tc = thread_coords(F.wave); const int ch = tc.tid & 127, tsub = tc.tid >> 7, win = 2 << (ch >> 5);
;     const int ts = t0 + tsub * 16; if (ts >= Tlen) return;
;     float acc[8];
; #pragma unroll
;     for (int e = 0; e < 8; ++e) acc[e] = 0.f;
; #pragma unroll
;     for (int j = 1; j < 16; ++j) if (j < win) { float v[8]; pool_row(F, layer, stream, b, rowbase, ts - j, ch, v);
; #pragma unroll
;         for (int e = 0; e < 8; ++e) acc[e] += v[e]; }
; #pragma unroll 4
;     for (int tt = 0; tt < 16; ++tt) {
;         const int t = ts + tt;
;         float vn[8], vo[8]; pool_row(F, layer, stream, b, rowbase, t, ch, vn);
.Lpool_fast_wide:
	v_mov_b32_e32 v4, 0x3e000000
	v_mov_b32_e32 v6, 0x3d800000
	v_cmp_gt_u32_e32 vcc, 32, v1
	s_nop 1
	v_cndmask_b32_e32 v4, v6, v4, vcc
	v_mov_b32_e32 v5, v4
	s_sub_u32 s24, s20, 0x1000
	s_subb_u32 s25, s21, 0
	global_load_dwordx4 v[76:79], v3, s[24:25] offset:2048
	global_load_dwordx4 v[72:75], v3, s[24:25]
	s_sub_u32 s24, s20, 0x2000
	s_subb_u32 s25, s21, 0
	global_load_dwordx4 v[68:71], v3, s[24:25] offset:2048
	global_load_dwordx4 v[64:67], v3, s[24:25]
	s_sub_u32 s24, s20, 0x3000
	s_subb_u32 s25, s21, 0
	global_load_dwordx4 v[60:63], v3, s[24:25] offset:2048
	global_load_dwordx4 v[56:59], v3, s[24:25]
	s_sub_u32 s24, s20, 0x4000
	s_subb_u32 s25, s21, 0
	global_load_dwordx4 v[52:55], v3, s[24:25] offset:2048
	global_load_dwordx4 v[48:51], v3, s[24:25]
	s_sub_u32 s24, s20, 0x5000
	s_subb_u32 s25, s21, 0
	global_load_dwordx4 v[44:47], v3, s[24:25] offset:2048
	global_load_dwordx4 v[40:43], v3, s[24:25]
	s_sub_u32 s24, s20, 0x6000
	s_subb_u32 s25, s21, 0
	global_load_dwordx4 v[36:39], v3, s[24:25] offset:2048
	global_load_dwordx4 v[32:35], v3, s[24:25]
	s_sub_u32 s24, s20, 0x7000
	s_subb_u32 s25, s21, 0
	global_load_dwordx4 v[28:31], v3, s[24:25] offset:2048
	global_load_dwordx4 v[24:27], v3, s[24:25]
	s_sub_u32 s24, s20, 0x7800
	s_subb_u32 s25, s21, 0
	global_load_dwordx4 v[20:23], v3, s[24:25]
	s_mov_b64 s[24:25], s[18:19]
	global_load_dwordx4 v[80:83], v3, s[24:25]
	global_load_dwordx4 v[84:87], v3, s[24:25] offset:2048
	s_add_u32 s24, s18, 0x1000
	s_addc_u32 s25, s19, 0
	global_load_dwordx4 v[88:91], v3, s[24:25]
	global_load_dwordx4 v[92:95], v3, s[24:25] offset:2048
	s_add_u32 s24, s18, 0x2000
	s_addc_u32 s25, s19, 0
	global_load_dwordx4 v[96:99], v3, s[24:25]
	global_load_dwordx4 v[100:103], v3, s[24:25] offset:2048
	s_add_u32 s24, s18, 0x3000
	s_addc_u32 s25, s19, 0
	global_load_dwordx4 v[104:107], v3, s[24:25]
	global_load_dwordx4 v[108:111], v3, s[24:25] offset:2048
	s_add_u32 s24, s18, 0x4000
	s_addc_u32 s25, s19, 0
	global_load_dwordx4 v[112:115], v3, s[24:25]
	global_load_dwordx4 v[116:119], v3, s[24:25] offset:2048
	s_add_u32 s24, s18, 0x5000
	s_addc_u32 s25, s19, 0
	global_load_dwordx4 v[120:123], v3, s[24:25]
	global_load_dwordx4 v[124:127], v3, s[24:25] offset:2048
	s_add_u32 s24, s18, 0x6000
	s_addc_u32 s25, s19, 0
	global_load_dwordx4 v[128:131], v3, s[24:25]
	global_load_dwordx4 v[132:135], v3, s[24:25] offset:2048
	s_add_u32 s24, s18, 0x7000
	s_addc_u32 s25, s19, 0
	global_load_dwordx4 v[136:139], v3, s[24:25]
	global_load_dwordx4 v[140:143], v3, s[24:25] offset:2048
	v_mov_b32_e32 v8, 0
	v_mov_b32_e32 v9, 0
	v_mov_b32_e32 v10, 0
	v_mov_b32_e32 v11, 0
	v_mov_b32_e32 v12, 0
	v_mov_b32_e32 v13, 0
	v_mov_b32_e32 v14, 0
	v_mov_b32_e32 v15, 0
	s_waitcnt vmcnt(30)
	v_lshlrev_b32_e32 v152, 16, v76
	v_and_b32_e32 v153, 0xffff0000, v76
	v_lshlrev_b32_e32 v154, 16, v77
	v_and_b32_e32 v155, 0xffff0000, v77
	v_lshlrev_b32_e32 v156, 16, v78
	v_and_b32_e32 v157, 0xffff0000, v78
	v_lshlrev_b32_e32 v158, 16, v79
	v_and_b32_e32 v159, 0xffff0000, v79
	v_pk_add_f32 v[8:9], v[8:9], v[152:153]
	v_pk_add_f32 v[10:11], v[10:11], v[154:155]
	v_pk_add_f32 v[12:13], v[12:13], v[156:157]
	v_pk_add_f32 v[14:15], v[14:15], v[158:159]
	s_waitcnt vmcnt(29)
	v_lshlrev_b32_e32 v152, 16, v72
	v_and_b32_e32 v153, 0xffff0000, v72
	v_lshlrev_b32_e32 v154, 16, v73
	v_and_b32_e32 v155, 0xffff0000, v73
	v_lshlrev_b32_e32 v156, 16, v74
	v_and_b32_e32 v157, 0xffff0000, v74
	v_lshlrev_b32_e32 v158, 16, v75
	v_and_b32_e32 v159, 0xffff0000, v75
	v_pk_add_f32 v[8:9], v[8:9], v[152:153]
	v_pk_add_f32 v[10:11], v[10:11], v[154:155]
	v_pk_add_f32 v[12:13], v[12:13], v[156:157]
	v_pk_add_f32 v[14:15], v[14:15], v[158:159]
	s_waitcnt vmcnt(28)
	v_lshlrev_b32_e32 v152, 16, v68
	v_and_b32_e32 v153, 0xffff0000, v68
	v_lshlrev_b32_e32 v154, 16, v69
	v_and_b32_e32 v155, 0xffff0000, v69
	v_lshlrev_b32_e32 v156, 16, v70
	v_and_b32_e32 v157, 0xffff0000, v70
	v_lshlrev_b32_e32 v158, 16, v71
	v_and_b32_e32 v159, 0xffff0000, v71
	v_pk_add_f32 v[8:9], v[8:9], v[152:153]
	v_pk_add_f32 v[10:11], v[10:11], v[154:155]
	v_pk_add_f32 v[12:13], v[12:13], v[156:157]
	v_pk_add_f32 v[14:15], v[14:15], v[158:159]
	s_waitcnt vmcnt(27)
	v_lshlrev_b32_e32 v152, 16, v64
	v_and_b32_e32 v153, 0xffff0000, v64
	v_lshlrev_b32_e32 v154, 16, v65
	v_and_b32_e32 v155, 0xffff0000, v65
	v_lshlrev_b32_e32 v156, 16, v66
	v_and_b32_e32 v157, 0xffff0000, v66
	v_lshlrev_b32_e32 v158, 16, v67
	v_and_b32_e32 v159, 0xffff0000, v67
	v_pk_add_f32 v[8:9], v[8:9], v[152:153]
	v_pk_add_f32 v[10:11], v[10:11], v[154:155]
	v_pk_add_f32 v[12:13], v[12:13], v[156:157]
	v_pk_add_f32 v[14:15], v[14:15], v[158:159]
	s_waitcnt vmcnt(26)
	v_lshlrev_b32_e32 v152, 16, v60
	v_and_b32_e32 v153, 0xffff0000, v60
	v_lshlrev_b32_e32 v154, 16, v61
	v_and_b32_e32 v155, 0xffff0000, v61
	v_lshlrev_b32_e32 v156, 16, v62
	v_and_b32_e32 v157, 0xffff0000, v62
	v_lshlrev_b32_e32 v158, 16, v63
	v_and_b32_e32 v159, 0xffff0000, v63
	v_pk_add_f32 v[8:9], v[8:9], v[152:153]
	v_pk_add_f32 v[10:11], v[10:11], v[154:155]
	v_pk_add_f32 v[12:13], v[12:13], v[156:157]
	v_pk_add_f32 v[14:15], v[14:15], v[158:159]
	s_waitcnt vmcnt(25)
	v_lshlrev_b32_e32 v152, 16, v56
	v_and_b32_e32 v153, 0xffff0000, v56
	v_lshlrev_b32_e32 v154, 16, v57
	v_and_b32_e32 v155, 0xffff0000, v57
	v_lshlrev_b32_e32 v156, 16, v58
	v_and_b32_e32 v157, 0xffff0000, v58
	v_lshlrev_b32_e32 v158, 16, v59
	v_and_b32_e32 v159, 0xffff0000, v59
	v_pk_add_f32 v[8:9], v[8:9], v[152:153]
	v_pk_add_f32 v[10:11], v[10:11], v[154:155]
	v_pk_add_f32 v[12:13], v[12:13], v[156:157]
	v_pk_add_f32 v[14:15], v[14:15], v[158:159]
	s_waitcnt vmcnt(24)
; #define GAS __attribute__((address_space(1)))
; __device__ __forceinline__ unsigned pk2(float lo, float hi) { return f2bf(lo) | (f2bf(hi) << 16); }
; #define WSB(F, off) ((bf16*)(wsq((F).ws) + (off)))
; __device__ __forceinline__ void pool_unit(const Frame& F, int layer, int uid) {
;     ...
;     for (int j = 1; j < 16; ++j) if (j < win) { float v[8]; pool_row(F, layer, stream, b, rowbase, ts - j, ch, v);
; #pragma unroll
;         for (int e = 0; e < 8; ++e) acc[e] += v[e]; }
; #pragma unroll 4
;     for (int tt = 0; tt < 16; ++tt) {
;         const int t = ts + tt;
;         float vn[8], vo[8]; pool_row(F, layer, stream, b, rowbase, t, ch, vn);
;         if (tt > 0) pool_row(F, layer, stream, b, rowbase, t - win, ch, vo);
; #pragma unroll
;         for (int e = 0; e < 8; ++e) acc[e] += vn[e] - (tt > 0 ? vo[e] : 0.f);
;         const int have = (stream == 2) ? (t + 1 < win ? t + 1 : win) : win;
;         const float inv = 1.0f / (float)have;
;         float y[8];
; #pragma unroll
;         for (int e = 0; e < 8; ++e) y[e] = acc[e] * inv - vn[e];
;         *(GAS v4u*)(WSB(F, WS_BR) + (size_t)2 * M_PAD * D + (size_t)(rowbase + t) * D + ch * 8) = (v4u){pk2(y[0], y[1]), pk2(y[2], y[3]), pk2(y[4], y[5]), pk2(y[6], y[7])};
	v_lshlrev_b32_e32 v152, 16, v52
	v_and_b32_e32 v153, 0xffff0000, v52
	v_lshlrev_b32_e32 v154, 16, v53
	v_and_b32_e32 v155, 0xffff0000, v53
	v_lshlrev_b32_e32 v156, 16, v54
	v_and_b32_e32 v157, 0xffff0000, v54
	v_lshlrev_b32_e32 v158, 16, v55
	v_and_b32_e32 v159, 0xffff0000, v55
	v_pk_add_f32 v[8:9], v[8:9], v[152:153]
	v_pk_add_f32 v[10:11], v[10:11], v[154:155]
	v_pk_add_f32 v[12:13], v[12:13], v[156:157]
	v_pk_add_f32 v[14:15], v[14:15], v[158:159]
	s_waitcnt vmcnt(23)
	v_lshlrev_b32_e32 v152, 16, v48
	v_and_b32_e32 v153, 0xffff0000, v48
	v_lshlrev_b32_e32 v154, 16, v49
	v_and_b32_e32 v155, 0xffff0000, v49
	v_lshlrev_b32_e32 v156, 16, v50
	v_and_b32_e32 v157, 0xffff0000, v50
	v_lshlrev_b32_e32 v158, 16, v51
	v_and_b32_e32 v159, 0xffff0000, v51
	s_mov_b64 exec, s[30:31]
	v_pk_add_f32 v[8:9], v[8:9], v[152:153]
	v_pk_add_f32 v[10:11], v[10:11], v[154:155]
	v_pk_add_f32 v[12:13], v[12:13], v[156:157]
	v_pk_add_f32 v[14:15], v[14:15], v[158:159]
	s_mov_b64 exec, -1
	s_waitcnt vmcnt(22)
	v_lshlrev_b32_e32 v152, 16, v44
	v_and_b32_e32 v153, 0xffff0000, v44
	v_lshlrev_b32_e32 v154, 16, v45
	v_and_b32_e32 v155, 0xffff0000, v45
	v_lshlrev_b32_e32 v156, 16, v46
	v_and_b32_e32 v157, 0xffff0000, v46
	v_lshlrev_b32_e32 v158, 16, v47
	v_and_b32_e32 v159, 0xffff0000, v47
	s_mov_b64 exec, s[30:31]
	v_pk_add_f32 v[8:9], v[8:9], v[152:153]
	v_pk_add_f32 v[10:11], v[10:11], v[154:155]
	v_pk_add_f32 v[12:13], v[12:13], v[156:157]
	v_pk_add_f32 v[14:15], v[14:15], v[158:159]
	s_mov_b64 exec, -1
	s_waitcnt vmcnt(21)
	v_lshlrev_b32_e32 v152, 16, v40
	v_and_b32_e32 v153, 0xffff0000, v40
	v_lshlrev_b32_e32 v154, 16, v41
	v_and_b32_e32 v155, 0xffff0000, v41
	v_lshlrev_b32_e32 v156, 16, v42
	v_and_b32_e32 v157, 0xffff0000, v42
	v_lshlrev_b32_e32 v158, 16, v43
	v_and_b32_e32 v159, 0xffff0000, v43
	s_mov_b64 exec, s[30:31]
	v_pk_add_f32 v[8:9], v[8:9], v[152:153]
	v_pk_add_f32 v[10:11], v[10:11], v[154:155]
	v_pk_add_f32 v[12:13], v[12:13], v[156:157]
	v_pk_add_f32 v[14:15], v[14:15], v[158:159]
	s_mov_b64 exec, -1
	s_waitcnt vmcnt(20)
	v_lshlrev_b32_e32 v152, 16, v36
	v_and_b32_e32 v153, 0xffff0000, v36
	v_lshlrev_b32_e32 v154, 16, v37
	v_and_b32_e32 v155, 0xffff0000, v37
	v_lshlrev_b32_e32 v156, 16, v38
	v_and_b32_e32 v157, 0xffff0000, v38
	v_lshlrev_b32_e32 v158, 16, v39
	v_and_b32_e32 v159, 0xffff0000, v39
	s_mov_b64 exec, s[30:31]
	v_pk_add_f32 v[8:9], v[8:9], v[152:153]
	v_pk_add_f32 v[10:11], v[10:11], v[154:155]
	v_pk_add_f32 v[12:13], v[12:13], v[156:157]
	v_pk_add_f32 v[14:15], v[14:15], v[158:159]
	s_mov_b64 exec, -1
	s_waitcnt vmcnt(19)
	v_lshlrev_b32_e32 v152, 16, v32
	v_and_b32_e32 v153, 0xffff0000, v32
	v_lshlrev_b32_e32 v154, 16, v33
	v_and_b32_e32 v155, 0xffff0000, v33
	v_lshlrev_b32_e32 v156, 16, v34
	v_and_b32_e32 v157, 0xffff0000, v34
	v_lshlrev_b32_e32 v158, 16, v35
	v_and_b32_e32 v159, 0xffff0000, v35
	s_mov_b64 exec, s[30:31]
	v_pk_add_f32 v[8:9], v[8:9], v[152:153]
	v_pk_add_f32 v[10:11], v[10:11], v[154:155]
	v_pk_add_f32 v[12:13], v[12:13], v[156:157]
	v_pk_add_f32 v[14:15], v[14:15], v[158:159]
	s_mov_b64 exec, -1
	s_waitcnt vmcnt(18)
	v_lshlrev_b32_e32 v152, 16, v28
	v_and_b32_e32 v153, 0xffff0000, v28
	v_lshlrev_b32_e32 v154, 16, v29
	v_and_b32_e32 v155, 0xffff0000, v29
	v_lshlrev_b32_e32 v156, 16, v30
	v_and_b32_e32 v157, 0xffff0000, v30
	v_lshlrev_b32_e32 v158, 16, v31
	v_and_b32_e32 v159, 0xffff0000, v31
	s_mov_b64 exec, s[30:31]
	v_pk_add_f32 v[8:9], v[8:9], v[152:153]
	v_pk_add_f32 v[10:11], v[10:11], v[154:155]
	v_pk_add_f32 v[12:13], v[12:13], v[156:157]
	v_pk_add_f32 v[14:15], v[14:15], v[158:159]
	s_mov_b64 exec, -1
	s_waitcnt vmcnt(17)
	v_lshlrev_b32_e32 v152, 16, v24
	v_and_b32_e32 v153, 0xffff0000, v24
	v_lshlrev_b32_e32 v154, 16, v25
	v_and_b32_e32 v155, 0xffff0000, v25
	v_lshlrev_b32_e32 v156, 16, v26
	v_and_b32_e32 v157, 0xffff0000, v26
	v_lshlrev_b32_e32 v158, 16, v27
	v_and_b32_e32 v159, 0xffff0000, v27
	s_mov_b64 exec, s[30:31]
	v_pk_add_f32 v[8:9], v[8:9], v[152:153]
	v_pk_add_f32 v[10:11], v[10:11], v[154:155]
	v_pk_add_f32 v[12:13], v[12:13], v[156:157]
	v_pk_add_f32 v[14:15], v[14:15], v[158:159]
	s_mov_b64 exec, -1
	s_waitcnt vmcnt(16)
	v_lshlrev_b32_e32 v152, 16, v20
	v_and_b32_e32 v153, 0xffff0000, v20
	v_lshlrev_b32_e32 v154, 16, v21
	v_and_b32_e32 v155, 0xffff0000, v21
	v_lshlrev_b32_e32 v156, 16, v22
	v_and_b32_e32 v157, 0xffff0000, v22
	v_lshlrev_b32_e32 v158, 16, v23
	v_and_b32_e32 v159, 0xffff0000, v23
	s_mov_b64 exec, s[30:31]
	v_pk_add_f32 v[8:9], v[8:9], v[152:153]
	v_pk_add_f32 v[10:11], v[10:11], v[154:155]
	v_pk_add_f32 v[12:13], v[12:13], v[156:157]
	v_pk_add_f32 v[14:15], v[14:15], v[158:159]
	s_mov_b64 exec, -1
	s_waitcnt vmcnt(15)
	v_lshlrev_b32_e32 v144, 16, v80
	v_and_b32_e32 v145, 0xffff0000, v80
	v_lshlrev_b32_e32 v146, 16, v81
	v_and_b32_e32 v147, 0xffff0000, v81
	v_lshlrev_b32_e32 v148, 16, v82
	v_and_b32_e32 v149, 0xffff0000, v82
	v_lshlrev_b32_e32 v150, 16, v83
	v_and_b32_e32 v151, 0xffff0000, v83
	v_pk_add_f32 v[8:9], v[8:9], v[144:145]
	v_pk_add_f32 v[10:11], v[10:11], v[146:147]
	v_pk_add_f32 v[12:13], v[12:13], v[148:149]
	v_pk_add_f32 v[14:15], v[14:15], v[150:151]
	v_pk_fma_f32 v[168:169], v[8:9], v[4:5], v[144:145] neg_lo:[0,0,1] neg_hi:[0,0,1]
	v_pk_fma_f32 v[170:171], v[10:11], v[4:5], v[146:147] neg_lo:[0,0,1] neg_hi:[0,0,1]
	v_pk_fma_f32 v[172:173], v[12:13], v[4:5], v[148:149] neg_lo:[0,0,1] neg_hi:[0,0,1]
	v_pk_fma_f32 v[174:175], v[14:15], v[4:5], v[150:151] neg_lo:[0,0,1] neg_hi:[0,0,1]
	v_cvt_pk_bf16_f32 v176, v168, v169
	v_cvt_pk_bf16_f32 v177, v170, v171
	v_cvt_pk_bf16_f32 v178, v172, v173
	v_cvt_pk_bf16_f32 v179, v174, v175
	s_mov_b64 s[26:27], s[22:23]
	s_nop 0
	global_store_dwordx4 v3, v[176:179], s[26:27]
	s_nop 1
	s_waitcnt vmcnt(15)
; #define GAS __attribute__((address_space(1)))
; __device__ __forceinline__ unsigned pk2(float lo, float hi) { return f2bf(lo) | (f2bf(hi) << 16); }
; #define WSB(F, off) ((bf16*)(wsq((F).ws) + (off)))
; __device__ __forceinline__ void pool_unit(const Frame& F, int layer, int uid) {
;     ...
;     for (int tt = 0; tt < 16; ++tt) {
;         const int t = ts + tt;
;         float vn[8], vo[8]; pool_row(F, layer, stream, b, rowbase, t, ch, vn);
;         if (tt > 0) pool_row(F, layer, stream, b, rowbase, t - win, ch, vo);
; #pragma unroll
;         for (int e = 0; e < 8; ++e) acc[e] += vn[e] - (tt > 0 ? vo[e] : 0.f);
;         const int have = (stream == 2) ? (t + 1 < win ? t + 1 : win) : win;
;         const float inv = 1.0f / (float)have;
;         float y[8];
; #pragma unroll
;         for (int e = 0; e < 8; ++e) y[e] = acc[e] * inv - vn[e];
;         *(GAS v4u*)(WSB(F, WS_BR) + (size_t)2 * M_PAD * D + (size_t)(rowbase + t) * D + ch * 8) = (v4u){pk2(y[0], y[1]), pk2(y[2], y[3]), pk2(y[4], y[5]), pk2(y[6], y[7])};
	v_lshlrev_b32_e32 v144, 16, v84
	v_and_b32_e32 v145, 0xffff0000, v84
	v_lshlrev_b32_e32 v146, 16, v85
	v_and_b32_e32 v147, 0xffff0000, v85
	v_lshlrev_b32_e32 v148, 16, v86
	v_and_b32_e32 v149, 0xffff0000, v86
	v_lshlrev_b32_e32 v150, 16, v87
	v_and_b32_e32 v151, 0xffff0000, v87
	v_lshlrev_b32_e32 v152, 16, v52
	v_and_b32_e32 v153, 0xffff0000, v52
	v_lshlrev_b32_e32 v154, 16, v53
	v_and_b32_e32 v155, 0xffff0000, v53
	v_lshlrev_b32_e32 v156, 16, v54
	v_and_b32_e32 v157, 0xffff0000, v54
	v_lshlrev_b32_e32 v158, 16, v55
	v_and_b32_e32 v159, 0xffff0000, v55
	s_mov_b64 exec, s[28:29]
	v_pk_add_f32 v[160:161], v[144:145], v[152:153] neg_lo:[0,1] neg_hi:[0,1]
	v_pk_add_f32 v[162:163], v[146:147], v[154:155] neg_lo:[0,1] neg_hi:[0,1]
	v_pk_add_f32 v[164:165], v[148:149], v[156:157] neg_lo:[0,1] neg_hi:[0,1]
	v_pk_add_f32 v[166:167], v[150:151], v[158:159] neg_lo:[0,1] neg_hi:[0,1]
	s_mov_b64 exec, -1
	v_lshlrev_b32_e32 v152, 16, v20
	v_and_b32_e32 v153, 0xffff0000, v20
	v_lshlrev_b32_e32 v154, 16, v21
	v_and_b32_e32 v155, 0xffff0000, v21
	v_lshlrev_b32_e32 v156, 16, v22
	v_and_b32_e32 v157, 0xffff0000, v22
	v_lshlrev_b32_e32 v158, 16, v23
	v_and_b32_e32 v159, 0xffff0000, v23
	s_mov_b64 exec, s[30:31]
	v_pk_add_f32 v[160:161], v[144:145], v[152:153] neg_lo:[0,1] neg_hi:[0,1]
	v_pk_add_f32 v[162:163], v[146:147], v[154:155] neg_lo:[0,1] neg_hi:[0,1]
	v_pk_add_f32 v[164:165], v[148:149], v[156:157] neg_lo:[0,1] neg_hi:[0,1]
	v_pk_add_f32 v[166:167], v[150:151], v[158:159] neg_lo:[0,1] neg_hi:[0,1]
	s_mov_b64 exec, -1
	v_pk_add_f32 v[8:9], v[8:9], v[160:161]
	v_pk_add_f32 v[10:11], v[10:11], v[162:163]
	v_pk_add_f32 v[12:13], v[12:13], v[164:165]
	v_pk_add_f32 v[14:15], v[14:15], v[166:167]
	v_pk_fma_f32 v[168:169], v[8:9], v[4:5], v[144:145] neg_lo:[0,0,1] neg_hi:[0,0,1]
	v_pk_fma_f32 v[170:171], v[10:11], v[4:5], v[146:147] neg_lo:[0,0,1] neg_hi:[0,0,1]
	v_pk_fma_f32 v[172:173], v[12:13], v[4:5], v[148:149] neg_lo:[0,0,1] neg_hi:[0,0,1]
	v_pk_fma_f32 v[174:175], v[14:15], v[4:5], v[150:151] neg_lo:[0,0,1] neg_hi:[0,0,1]
	v_cvt_pk_bf16_f32 v176, v168, v169
	v_cvt_pk_bf16_f32 v177, v170, v171
	v_cvt_pk_bf16_f32 v178, v172, v173
	v_cvt_pk_bf16_f32 v179, v174, v175
	s_nop 0
	global_store_dwordx4 v3, v[176:179], s[26:27] offset:2048
	s_nop 1
	s_waitcnt vmcnt(15)
	v_lshlrev_b32_e32 v144, 16, v88
	v_and_b32_e32 v145, 0xffff0000, v88
	v_lshlrev_b32_e32 v146, 16, v89
	v_and_b32_e32 v147, 0xffff0000, v89
	v_lshlrev_b32_e32 v148, 16, v90
	v_and_b32_e32 v149, 0xffff0000, v90
	v_lshlrev_b32_e32 v150, 16, v91
	v_and_b32_e32 v151, 0xffff0000, v91
	v_lshlrev_b32_e32 v152, 16, v56
	v_and_b32_e32 v153, 0xffff0000, v56
	v_lshlrev_b32_e32 v154, 16, v57
	v_and_b32_e32 v155, 0xffff0000, v57
	v_lshlrev_b32_e32 v156, 16, v58
	v_and_b32_e32 v157, 0xffff0000, v58
	v_lshlrev_b32_e32 v158, 16, v59
	v_and_b32_e32 v159, 0xffff0000, v59
	s_mov_b64 exec, s[28:29]
	v_pk_add_f32 v[160:161], v[144:145], v[152:153] neg_lo:[0,1] neg_hi:[0,1]
	v_pk_add_f32 v[162:163], v[146:147], v[154:155] neg_lo:[0,1] neg_hi:[0,1]
	v_pk_add_f32 v[164:165], v[148:149], v[156:157] neg_lo:[0,1] neg_hi:[0,1]
	v_pk_add_f32 v[166:167], v[150:151], v[158:159] neg_lo:[0,1] neg_hi:[0,1]
	s_mov_b64 exec, -1
	v_lshlrev_b32_e32 v152, 16, v24
	v_and_b32_e32 v153, 0xffff0000, v24
	v_lshlrev_b32_e32 v154, 16, v25
	v_and_b32_e32 v155, 0xffff0000, v25
	v_lshlrev_b32_e32 v156, 16, v26
	v_and_b32_e32 v157, 0xffff0000, v26
	v_lshlrev_b32_e32 v158, 16, v27
	v_and_b32_e32 v159, 0xffff0000, v27
	s_mov_b64 exec, s[30:31]
	v_pk_add_f32 v[160:161], v[144:145], v[152:153] neg_lo:[0,1] neg_hi:[0,1]
	v_pk_add_f32 v[162:163], v[146:147], v[154:155] neg_lo:[0,1] neg_hi:[0,1]
	v_pk_add_f32 v[164:165], v[148:149], v[156:157] neg_lo:[0,1] neg_hi:[0,1]
	v_pk_add_f32 v[166:167], v[150:151], v[158:159] neg_lo:[0,1] neg_hi:[0,1]
	s_mov_b64 exec, -1
	v_pk_add_f32 v[8:9], v[8:9], v[160:161]
	v_pk_add_f32 v[10:11], v[10:11], v[162:163]
	v_pk_add_f32 v[12:13], v[12:13], v[164:165]
	v_pk_add_f32 v[14:15], v[14:15], v[166:167]
	v_pk_fma_f32 v[168:169], v[8:9], v[4:5], v[144:145] neg_lo:[0,0,1] neg_hi:[0,0,1]
	v_pk_fma_f32 v[170:171], v[10:11], v[4:5], v[146:147] neg_lo:[0,0,1] neg_hi:[0,0,1]
	v_pk_fma_f32 v[172:173], v[12:13], v[4:5], v[148:149] neg_lo:[0,0,1] neg_hi:[0,0,1]
	v_pk_fma_f32 v[174:175], v[14:15], v[4:5], v[150:151] neg_lo:[0,0,1] neg_hi:[0,0,1]
	v_cvt_pk_bf16_f32 v176, v168, v169
	v_cvt_pk_bf16_f32 v177, v170, v171
	v_cvt_pk_bf16_f32 v178, v172, v173
	v_cvt_pk_bf16_f32 v179, v174, v175
	s_add_u32 s26, s22, 0x1000
	s_addc_u32 s27, s23, 0
	s_nop 0
	global_store_dwordx4 v3, v[176:179], s[26:27]
	s_nop 1
	s_waitcnt vmcnt(15)
; #define GAS __attribute__((address_space(1)))
; __device__ __forceinline__ unsigned pk2(float lo, float hi) { return f2bf(lo) | (f2bf(hi) << 16); }
; #define WSB(F, off) ((bf16*)(wsq((F).ws) + (off)))
; __device__ __forceinline__ void pool_unit(const Frame& F, int layer, int uid) {
;     ...
;     for (int tt = 0; tt < 16; ++tt) {
;         const int t = ts + tt;
;         float vn[8], vo[8]; pool_row(F, layer, stream, b, rowbase, t, ch, vn);
;         if (tt > 0) pool_row(F, layer, stream, b, rowbase, t - win, ch, vo);
; #pragma unroll
;         for (int e = 0; e < 8; ++e) acc[e] += vn[e] - (tt > 0 ? vo[e] : 0.f);
;         const int have = (stream == 2) ? (t + 1 < win ? t + 1 : win) : win;
;         const float inv = 1.0f / (float)have;
;         float y[8];
; #pragma unroll
;         for (int e = 0; e < 8; ++e) y[e] = acc[e] * inv - vn[e];
;         *(GAS v4u*)(WSB(F, WS_BR) + (size_t)2 * M_PAD * D + (size_t)(rowbase + t) * D + ch * 8) = (v4u){pk2(y[0], y[1]), pk2(y[2], y[3]), pk2(y[4], y[5]), pk2(y[6], y[7])};
	v_lshlrev_b32_e32 v144, 16, v92
	v_and_b32_e32 v145, 0xffff0000, v92
	v_lshlrev_b32_e32 v146, 16, v93
	v_and_b32_e32 v147, 0xffff0000, v93
	v_lshlrev_b32_e32 v148, 16, v94
	v_and_b32_e32 v149, 0xffff0000, v94
	v_lshlrev_b32_e32 v150, 16, v95
	v_and_b32_e32 v151, 0xffff0000, v95
	v_lshlrev_b32_e32 v152, 16, v60
	v_and_b32_e32 v153, 0xffff0000, v60
	v_lshlrev_b32_e32 v154, 16, v61
	v_and_b32_e32 v155, 0xffff0000, v61
	v_lshlrev_b32_e32 v156, 16, v62
	v_and_b32_e32 v157, 0xffff0000, v62
	v_lshlrev_b32_e32 v158, 16, v63
	v_and_b32_e32 v159, 0xffff0000, v63
	s_mov_b64 exec, s[28:29]
	v_pk_add_f32 v[160:161], v[144:145], v[152:153] neg_lo:[0,1] neg_hi:[0,1]
	v_pk_add_f32 v[162:163], v[146:147], v[154:155] neg_lo:[0,1] neg_hi:[0,1]
	v_pk_add_f32 v[164:165], v[148:149], v[156:157] neg_lo:[0,1] neg_hi:[0,1]
	v_pk_add_f32 v[166:167], v[150:151], v[158:159] neg_lo:[0,1] neg_hi:[0,1]
	s_mov_b64 exec, -1
	v_lshlrev_b32_e32 v152, 16, v28
	v_and_b32_e32 v153, 0xffff0000, v28
	v_lshlrev_b32_e32 v154, 16, v29
	v_and_b32_e32 v155, 0xffff0000, v29
	v_lshlrev_b32_e32 v156, 16, v30
	v_and_b32_e32 v157, 0xffff0000, v30
	v_lshlrev_b32_e32 v158, 16, v31
	v_and_b32_e32 v159, 0xffff0000, v31
	s_mov_b64 exec, s[30:31]
	v_pk_add_f32 v[160:161], v[144:145], v[152:153] neg_lo:[0,1] neg_hi:[0,1]
	v_pk_add_f32 v[162:163], v[146:147], v[154:155] neg_lo:[0,1] neg_hi:[0,1]
	v_pk_add_f32 v[164:165], v[148:149], v[156:157] neg_lo:[0,1] neg_hi:[0,1]
	v_pk_add_f32 v[166:167], v[150:151], v[158:159] neg_lo:[0,1] neg_hi:[0,1]
	s_mov_b64 exec, -1
	v_pk_add_f32 v[8:9], v[8:9], v[160:161]
	v_pk_add_f32 v[10:11], v[10:11], v[162:163]
	v_pk_add_f32 v[12:13], v[12:13], v[164:165]
	v_pk_add_f32 v[14:15], v[14:15], v[166:167]
	v_pk_fma_f32 v[168:169], v[8:9], v[4:5], v[144:145] neg_lo:[0,0,1] neg_hi:[0,0,1]
	v_pk_fma_f32 v[170:171], v[10:11], v[4:5], v[146:147] neg_lo:[0,0,1] neg_hi:[0,0,1]
	v_pk_fma_f32 v[172:173], v[12:13], v[4:5], v[148:149] neg_lo:[0,0,1] neg_hi:[0,0,1]
	v_pk_fma_f32 v[174:175], v[14:15], v[4:5], v[150:151] neg_lo:[0,0,1] neg_hi:[0,0,1]
	v_cvt_pk_bf16_f32 v176, v168, v169
	v_cvt_pk_bf16_f32 v177, v170, v171
	v_cvt_pk_bf16_f32 v178, v172, v173
	v_cvt_pk_bf16_f32 v179, v174, v175
	s_nop 0
	global_store_dwordx4 v3, v[176:179], s[26:27] offset:2048
	s_nop 1
	s_waitcnt vmcnt(15)
	v_lshlrev_b32_e32 v144, 16, v96
	v_and_b32_e32 v145, 0xffff0000, v96
	v_lshlrev_b32_e32 v146, 16, v97
	v_and_b32_e32 v147, 0xffff0000, v97
	v_lshlrev_b32_e32 v148, 16, v98
	v_and_b32_e32 v149, 0xffff0000, v98
	v_lshlrev_b32_e32 v150, 16, v99
	v_and_b32_e32 v151, 0xffff0000, v99
	v_lshlrev_b32_e32 v152, 16, v64
	v_and_b32_e32 v153, 0xffff0000, v64
	v_lshlrev_b32_e32 v154, 16, v65
	v_and_b32_e32 v155, 0xffff0000, v65
	v_lshlrev_b32_e32 v156, 16, v66
	v_and_b32_e32 v157, 0xffff0000, v66
	v_lshlrev_b32_e32 v158, 16, v67
	v_and_b32_e32 v159, 0xffff0000, v67
	s_mov_b64 exec, s[28:29]
	v_pk_add_f32 v[160:161], v[144:145], v[152:153] neg_lo:[0,1] neg_hi:[0,1]
	v_pk_add_f32 v[162:163], v[146:147], v[154:155] neg_lo:[0,1] neg_hi:[0,1]
	v_pk_add_f32 v[164:165], v[148:149], v[156:157] neg_lo:[0,1] neg_hi:[0,1]
	v_pk_add_f32 v[166:167], v[150:151], v[158:159] neg_lo:[0,1] neg_hi:[0,1]
	s_mov_b64 exec, -1
	v_lshlrev_b32_e32 v152, 16, v32
	v_and_b32_e32 v153, 0xffff0000, v32
	v_lshlrev_b32_e32 v154, 16, v33
	v_and_b32_e32 v155, 0xffff0000, v33
	v_lshlrev_b32_e32 v156, 16, v34
	v_and_b32_e32 v157, 0xffff0000, v34
	v_lshlrev_b32_e32 v158, 16, v35
	v_and_b32_e32 v159, 0xffff0000, v35
	s_mov_b64 exec, s[30:31]
	v_pk_add_f32 v[160:161], v[144:145], v[152:153] neg_lo:[0,1] neg_hi:[0,1]
	v_pk_add_f32 v[162:163], v[146:147], v[154:155] neg_lo:[0,1] neg_hi:[0,1]
	v_pk_add_f32 v[164:165], v[148:149], v[156:157] neg_lo:[0,1] neg_hi:[0,1]
	v_pk_add_f32 v[166:167], v[150:151], v[158:159] neg_lo:[0,1] neg_hi:[0,1]
	s_mov_b64 exec, -1
	v_pk_add_f32 v[8:9], v[8:9], v[160:161]
	v_pk_add_f32 v[10:11], v[10:11], v[162:163]
	v_pk_add_f32 v[12:13], v[12:13], v[164:165]
	v_pk_add_f32 v[14:15], v[14:15], v[166:167]
	v_pk_fma_f32 v[168:169], v[8:9], v[4:5], v[144:145] neg_lo:[0,0,1] neg_hi:[0,0,1]
	v_pk_fma_f32 v[170:171], v[10:11], v[4:5], v[146:147] neg_lo:[0,0,1] neg_hi:[0,0,1]
	v_pk_fma_f32 v[172:173], v[12:13], v[4:5], v[148:149] neg_lo:[0,0,1] neg_hi:[0,0,1]
	v_pk_fma_f32 v[174:175], v[14:15], v[4:5], v[150:151] neg_lo:[0,0,1] neg_hi:[0,0,1]
	v_cvt_pk_bf16_f32 v176, v168, v169
	v_cvt_pk_bf16_f32 v177, v170, v171
	v_cvt_pk_bf16_f32 v178, v172, v173
	v_cvt_pk_bf16_f32 v179, v174, v175
	s_add_u32 s26, s22, 0x2000
	s_addc_u32 s27, s23, 0
	s_nop 0
	global_store_dwordx4 v3, v[176:179], s[26:27]
	s_nop 1
	s_waitcnt vmcnt(15)
; #define GAS __attribute__((address_space(1)))
; __device__ __forceinline__ unsigned pk2(float lo, float hi) { return f2bf(lo) | (f2bf(hi) << 16); }
; #define WSB(F, off) ((bf16*)(wsq((F).ws) + (off)))
; __device__ __forceinline__ void pool_unit(const Frame& F, int layer, int uid) {
;     ...
;     for (int tt = 0; tt < 16; ++tt) {
;         const int t = ts + tt;
;         float vn[8], vo[8]; pool_row(F, layer, stream, b, rowbase, t, ch, vn);
;         if (tt > 0) pool_row(F, layer, stream, b, rowbase, t - win, ch, vo);
; #pragma unroll
;         for (int e = 0; e < 8; ++e) acc[e] += vn[e] - (tt > 0 ? vo[e] : 0.f);
;         const int have = (stream == 2) ? (t + 1 < win ? t + 1 : win) : win;
;         const float inv = 1.0f / (float)have;
;         float y[8];
; #pragma unroll
;         for (int e = 0; e < 8; ++e) y[e] = acc[e] * inv - vn[e];
;         *(GAS v4u*)(WSB(F, WS_BR) + (size_t)2 * M_PAD * D + (size_t)(rowbase + t) * D + ch * 8) = (v4u){pk2(y[0], y[1]), pk2(y[2], y[3]), pk2(y[4], y[5]), pk2(y[6], y[7])};
	v_lshlrev_b32_e32 v144, 16, v100
	v_and_b32_e32 v145, 0xffff0000, v100
	v_lshlrev_b32_e32 v146, 16, v101
	v_and_b32_e32 v147, 0xffff0000, v101
	v_lshlrev_b32_e32 v148, 16, v102
	v_and_b32_e32 v149, 0xffff0000, v102
	v_lshlrev_b32_e32 v150, 16, v103
	v_and_b32_e32 v151, 0xffff0000, v103
	v_lshlrev_b32_e32 v152, 16, v68
	v_and_b32_e32 v153, 0xffff0000, v68
	v_lshlrev_b32_e32 v154, 16, v69
	v_and_b32_e32 v155, 0xffff0000, v69
	v_lshlrev_b32_e32 v156, 16, v70
	v_and_b32_e32 v157, 0xffff0000, v70
	v_lshlrev_b32_e32 v158, 16, v71
	v_and_b32_e32 v159, 0xffff0000, v71
	s_mov_b64 exec, s[28:29]
	v_pk_add_f32 v[160:161], v[144:145], v[152:153] neg_lo:[0,1] neg_hi:[0,1]
	v_pk_add_f32 v[162:163], v[146:147], v[154:155] neg_lo:[0,1] neg_hi:[0,1]
	v_pk_add_f32 v[164:165], v[148:149], v[156:157] neg_lo:[0,1] neg_hi:[0,1]
	v_pk_add_f32 v[166:167], v[150:151], v[158:159] neg_lo:[0,1] neg_hi:[0,1]
	s_mov_b64 exec, -1
	v_lshlrev_b32_e32 v152, 16, v36
	v_and_b32_e32 v153, 0xffff0000, v36
	v_lshlrev_b32_e32 v154, 16, v37
	v_and_b32_e32 v155, 0xffff0000, v37
	v_lshlrev_b32_e32 v156, 16, v38
	v_and_b32_e32 v157, 0xffff0000, v38
	v_lshlrev_b32_e32 v158, 16, v39
	v_and_b32_e32 v159, 0xffff0000, v39
	s_mov_b64 exec, s[30:31]
	v_pk_add_f32 v[160:161], v[144:145], v[152:153] neg_lo:[0,1] neg_hi:[0,1]
	v_pk_add_f32 v[162:163], v[146:147], v[154:155] neg_lo:[0,1] neg_hi:[0,1]
	v_pk_add_f32 v[164:165], v[148:149], v[156:157] neg_lo:[0,1] neg_hi:[0,1]
	v_pk_add_f32 v[166:167], v[150:151], v[158:159] neg_lo:[0,1] neg_hi:[0,1]
	s_mov_b64 exec, -1
	v_pk_add_f32 v[8:9], v[8:9], v[160:161]
	v_pk_add_f32 v[10:11], v[10:11], v[162:163]
	v_pk_add_f32 v[12:13], v[12:13], v[164:165]
	v_pk_add_f32 v[14:15], v[14:15], v[166:167]
	v_pk_fma_f32 v[168:169], v[8:9], v[4:5], v[144:145] neg_lo:[0,0,1] neg_hi:[0,0,1]
	v_pk_fma_f32 v[170:171], v[10:11], v[4:5], v[146:147] neg_lo:[0,0,1] neg_hi:[0,0,1]
	v_pk_fma_f32 v[172:173], v[12:13], v[4:5], v[148:149] neg_lo:[0,0,1] neg_hi:[0,0,1]
	v_pk_fma_f32 v[174:175], v[14:15], v[4:5], v[150:151] neg_lo:[0,0,1] neg_hi:[0,0,1]
	v_cvt_pk_bf16_f32 v176, v168, v169
	v_cvt_pk_bf16_f32 v177, v170, v171
	v_cvt_pk_bf16_f32 v178, v172, v173
	v_cvt_pk_bf16_f32 v179, v174, v175
	s_nop 0
	global_store_dwordx4 v3, v[176:179], s[26:27] offset:2048
	s_nop 1
	s_waitcnt vmcnt(15)
	v_lshlrev_b32_e32 v144, 16, v104
	v_and_b32_e32 v145, 0xffff0000, v104
	v_lshlrev_b32_e32 v146, 16, v105
	v_and_b32_e32 v147, 0xffff0000, v105
	v_lshlrev_b32_e32 v148, 16, v106
	v_and_b32_e32 v149, 0xffff0000, v106
	v_lshlrev_b32_e32 v150, 16, v107
	v_and_b32_e32 v151, 0xffff0000, v107
	v_lshlrev_b32_e32 v152, 16, v72
	v_and_b32_e32 v153, 0xffff0000, v72
	v_lshlrev_b32_e32 v154, 16, v73
	v_and_b32_e32 v155, 0xffff0000, v73
	v_lshlrev_b32_e32 v156, 16, v74
	v_and_b32_e32 v157, 0xffff0000, v74
	v_lshlrev_b32_e32 v158, 16, v75
	v_and_b32_e32 v159, 0xffff0000, v75
	s_mov_b64 exec, s[28:29]
	v_pk_add_f32 v[160:161], v[144:145], v[152:153] neg_lo:[0,1] neg_hi:[0,1]
	v_pk_add_f32 v[162:163], v[146:147], v[154:155] neg_lo:[0,1] neg_hi:[0,1]
	v_pk_add_f32 v[164:165], v[148:149], v[156:157] neg_lo:[0,1] neg_hi:[0,1]
	v_pk_add_f32 v[166:167], v[150:151], v[158:159] neg_lo:[0,1] neg_hi:[0,1]
	s_mov_b64 exec, -1
	v_lshlrev_b32_e32 v152, 16, v40
	v_and_b32_e32 v153, 0xffff0000, v40
	v_lshlrev_b32_e32 v154, 16, v41
	v_and_b32_e32 v155, 0xffff0000, v41
	v_lshlrev_b32_e32 v156, 16, v42
	v_and_b32_e32 v157, 0xffff0000, v42
	v_lshlrev_b32_e32 v158, 16, v43
	v_and_b32_e32 v159, 0xffff0000, v43
	s_mov_b64 exec, s[30:31]
	v_pk_add_f32 v[160:161], v[144:145], v[152:153] neg_lo:[0,1] neg_hi:[0,1]
	v_pk_add_f32 v[162:163], v[146:147], v[154:155] neg_lo:[0,1] neg_hi:[0,1]
	v_pk_add_f32 v[164:165], v[148:149], v[156:157] neg_lo:[0,1] neg_hi:[0,1]
	v_pk_add_f32 v[166:167], v[150:151], v[158:159] neg_lo:[0,1] neg_hi:[0,1]
	s_mov_b64 exec, -1
	v_pk_add_f32 v[8:9], v[8:9], v[160:161]
	v_pk_add_f32 v[10:11], v[10:11], v[162:163]
	v_pk_add_f32 v[12:13], v[12:13], v[164:165]
	v_pk_add_f32 v[14:15], v[14:15], v[166:167]
	v_pk_fma_f32 v[168:169], v[8:9], v[4:5], v[144:145] neg_lo:[0,0,1] neg_hi:[0,0,1]
	v_pk_fma_f32 v[170:171], v[10:11], v[4:5], v[146:147] neg_lo:[0,0,1] neg_hi:[0,0,1]
	v_pk_fma_f32 v[172:173], v[12:13], v[4:5], v[148:149] neg_lo:[0,0,1] neg_hi:[0,0,1]
	v_pk_fma_f32 v[174:175], v[14:15], v[4:5], v[150:151] neg_lo:[0,0,1] neg_hi:[0,0,1]
	v_cvt_pk_bf16_f32 v176, v168, v169
	v_cvt_pk_bf16_f32 v177, v170, v171
	v_cvt_pk_bf16_f32 v178, v172, v173
	v_cvt_pk_bf16_f32 v179, v174, v175
	s_add_u32 s26, s22, 0x3000
	s_addc_u32 s27, s23, 0
	s_nop 0
	global_store_dwordx4 v3, v[176:179], s[26:27]
	s_nop 1
	s_waitcnt vmcnt(15)
; #define GAS __attribute__((address_space(1)))
; __device__ __forceinline__ unsigned pk2(float lo, float hi) { return f2bf(lo) | (f2bf(hi) << 16); }
; #define WSB(F, off) ((bf16*)(wsq((F).ws) + (off)))
; __device__ __forceinline__ void pool_unit(const Frame& F, int layer, int uid) {
;     ...
;     for (int tt = 0; tt < 16; ++tt) {
;         const int t = ts + tt;
;         float vn[8], vo[8]; pool_row(F, layer, stream, b, rowbase, t, ch, vn);
;         if (tt > 0) pool_row(F, layer, stream, b, rowbase, t - win, ch, vo);
; #pragma unroll
;         for (int e = 0; e < 8; ++e) acc[e] += vn[e] - (tt > 0 ? vo[e] : 0.f);
;         const int have = (stream == 2) ? (t + 1 < win ? t + 1 : win) : win;
;         const float inv = 1.0f / (float)have;
;         float y[8];
; #pragma unroll
;         for (int e = 0; e < 8; ++e) y[e] = acc[e] * inv - vn[e];
;         *(GAS v4u*)(WSB(F, WS_BR) + (size_t)2 * M_PAD * D + (size_t)(rowbase + t) * D + ch * 8) = (v4u){pk2(y[0], y[1]), pk2(y[2], y[3]), pk2(y[4], y[5]), pk2(y[6], y[7])};
	v_lshlrev_b32_e32 v144, 16, v108
	v_and_b32_e32 v145, 0xffff0000, v108
	v_lshlrev_b32_e32 v146, 16, v109
	v_and_b32_e32 v147, 0xffff0000, v109
	v_lshlrev_b32_e32 v148, 16, v110
	v_and_b32_e32 v149, 0xffff0000, v110
	v_lshlrev_b32_e32 v150, 16, v111
	v_and_b32_e32 v151, 0xffff0000, v111
	v_lshlrev_b32_e32 v152, 16, v76
	v_and_b32_e32 v153, 0xffff0000, v76
	v_lshlrev_b32_e32 v154, 16, v77
	v_and_b32_e32 v155, 0xffff0000, v77
	v_lshlrev_b32_e32 v156, 16, v78
	v_and_b32_e32 v157, 0xffff0000, v78
	v_lshlrev_b32_e32 v158, 16, v79
	v_and_b32_e32 v159, 0xffff0000, v79
	s_mov_b64 exec, s[28:29]
	v_pk_add_f32 v[160:161], v[144:145], v[152:153] neg_lo:[0,1] neg_hi:[0,1]
	v_pk_add_f32 v[162:163], v[146:147], v[154:155] neg_lo:[0,1] neg_hi:[0,1]
	v_pk_add_f32 v[164:165], v[148:149], v[156:157] neg_lo:[0,1] neg_hi:[0,1]
	v_pk_add_f32 v[166:167], v[150:151], v[158:159] neg_lo:[0,1] neg_hi:[0,1]
	s_mov_b64 exec, -1
	v_lshlrev_b32_e32 v152, 16, v44
	v_and_b32_e32 v153, 0xffff0000, v44
	v_lshlrev_b32_e32 v154, 16, v45
	v_and_b32_e32 v155, 0xffff0000, v45
	v_lshlrev_b32_e32 v156, 16, v46
	v_and_b32_e32 v157, 0xffff0000, v46
	v_lshlrev_b32_e32 v158, 16, v47
	v_and_b32_e32 v159, 0xffff0000, v47
	s_mov_b64 exec, s[30:31]
	v_pk_add_f32 v[160:161], v[144:145], v[152:153] neg_lo:[0,1] neg_hi:[0,1]
	v_pk_add_f32 v[162:163], v[146:147], v[154:155] neg_lo:[0,1] neg_hi:[0,1]
	v_pk_add_f32 v[164:165], v[148:149], v[156:157] neg_lo:[0,1] neg_hi:[0,1]
	v_pk_add_f32 v[166:167], v[150:151], v[158:159] neg_lo:[0,1] neg_hi:[0,1]
	s_mov_b64 exec, -1
	v_pk_add_f32 v[8:9], v[8:9], v[160:161]
	v_pk_add_f32 v[10:11], v[10:11], v[162:163]
	v_pk_add_f32 v[12:13], v[12:13], v[164:165]
	v_pk_add_f32 v[14:15], v[14:15], v[166:167]
	v_pk_fma_f32 v[168:169], v[8:9], v[4:5], v[144:145] neg_lo:[0,0,1] neg_hi:[0,0,1]
	v_pk_fma_f32 v[170:171], v[10:11], v[4:5], v[146:147] neg_lo:[0,0,1] neg_hi:[0,0,1]
	v_pk_fma_f32 v[172:173], v[12:13], v[4:5], v[148:149] neg_lo:[0,0,1] neg_hi:[0,0,1]
	v_pk_fma_f32 v[174:175], v[14:15], v[4:5], v[150:151] neg_lo:[0,0,1] neg_hi:[0,0,1]
	v_cvt_pk_bf16_f32 v176, v168, v169
	v_cvt_pk_bf16_f32 v177, v170, v171
	v_cvt_pk_bf16_f32 v178, v172, v173
	v_cvt_pk_bf16_f32 v179, v174, v175
	s_nop 0
	global_store_dwordx4 v3, v[176:179], s[26:27] offset:2048
	s_nop 1
	s_waitcnt vmcnt(15)
	v_lshlrev_b32_e32 v144, 16, v112
	v_and_b32_e32 v145, 0xffff0000, v112
	v_lshlrev_b32_e32 v146, 16, v113
	v_and_b32_e32 v147, 0xffff0000, v113
	v_lshlrev_b32_e32 v148, 16, v114
	v_and_b32_e32 v149, 0xffff0000, v114
	v_lshlrev_b32_e32 v150, 16, v115
	v_and_b32_e32 v151, 0xffff0000, v115
	v_lshlrev_b32_e32 v152, 16, v80
	v_and_b32_e32 v153, 0xffff0000, v80
	v_lshlrev_b32_e32 v154, 16, v81
	v_and_b32_e32 v155, 0xffff0000, v81
	v_lshlrev_b32_e32 v156, 16, v82
	v_and_b32_e32 v157, 0xffff0000, v82
	v_lshlrev_b32_e32 v158, 16, v83
	v_and_b32_e32 v159, 0xffff0000, v83
	s_mov_b64 exec, s[28:29]
	v_pk_add_f32 v[160:161], v[144:145], v[152:153] neg_lo:[0,1] neg_hi:[0,1]
	v_pk_add_f32 v[162:163], v[146:147], v[154:155] neg_lo:[0,1] neg_hi:[0,1]
	v_pk_add_f32 v[164:165], v[148:149], v[156:157] neg_lo:[0,1] neg_hi:[0,1]
	v_pk_add_f32 v[166:167], v[150:151], v[158:159] neg_lo:[0,1] neg_hi:[0,1]
	s_mov_b64 exec, -1
	v_lshlrev_b32_e32 v152, 16, v48
	v_and_b32_e32 v153, 0xffff0000, v48
	v_lshlrev_b32_e32 v154, 16, v49
	v_and_b32_e32 v155, 0xffff0000, v49
	v_lshlrev_b32_e32 v156, 16, v50
	v_and_b32_e32 v157, 0xffff0000, v50
	v_lshlrev_b32_e32 v158, 16, v51
	v_and_b32_e32 v159, 0xffff0000, v51
	s_mov_b64 exec, s[30:31]
	v_pk_add_f32 v[160:161], v[144:145], v[152:153] neg_lo:[0,1] neg_hi:[0,1]
	v_pk_add_f32 v[162:163], v[146:147], v[154:155] neg_lo:[0,1] neg_hi:[0,1]
	v_pk_add_f32 v[164:165], v[148:149], v[156:157] neg_lo:[0,1] neg_hi:[0,1]
	v_pk_add_f32 v[166:167], v[150:151], v[158:159] neg_lo:[0,1] neg_hi:[0,1]
	s_mov_b64 exec, -1
	v_pk_add_f32 v[8:9], v[8:9], v[160:161]
	v_pk_add_f32 v[10:11], v[10:11], v[162:163]
	v_pk_add_f32 v[12:13], v[12:13], v[164:165]
	v_pk_add_f32 v[14:15], v[14:15], v[166:167]
	v_pk_fma_f32 v[168:169], v[8:9], v[4:5], v[144:145] neg_lo:[0,0,1] neg_hi:[0,0,1]
	v_pk_fma_f32 v[170:171], v[10:11], v[4:5], v[146:147] neg_lo:[0,0,1] neg_hi:[0,0,1]
	v_pk_fma_f32 v[172:173], v[12:13], v[4:5], v[148:149] neg_lo:[0,0,1] neg_hi:[0,0,1]
	v_pk_fma_f32 v[174:175], v[14:15], v[4:5], v[150:151] neg_lo:[0,0,1] neg_hi:[0,0,1]
	v_cvt_pk_bf16_f32 v176, v168, v169
	v_cvt_pk_bf16_f32 v177, v170, v171
	v_cvt_pk_bf16_f32 v178, v172, v173
	v_cvt_pk_bf16_f32 v179, v174, v175
	s_add_u32 s26, s22, 0x4000
	s_addc_u32 s27, s23, 0
	s_nop 0
	global_store_dwordx4 v3, v[176:179], s[26:27]
	s_nop 1
	s_waitcnt vmcnt(15)
; #define GAS __attribute__((address_space(1)))
; __device__ __forceinline__ unsigned pk2(float lo, float hi) { return f2bf(lo) | (f2bf(hi) << 16); }
; #define WSB(F, off) ((bf16*)(wsq((F).ws) + (off)))
; __device__ __forceinline__ void pool_unit(const Frame& F, int layer, int uid) {
;     ...
;     for (int tt = 0; tt < 16; ++tt) {
;         const int t = ts + tt;
;         float vn[8], vo[8]; pool_row(F, layer, stream, b, rowbase, t, ch, vn);
;         if (tt > 0) pool_row(F, layer, stream, b, rowbase, t - win, ch, vo);
; #pragma unroll
;         for (int e = 0; e < 8; ++e) acc[e] += vn[e] - (tt > 0 ? vo[e] : 0.f);
;         const int have = (stream == 2) ? (t + 1 < win ? t + 1 : win) : win;
;         const float inv = 1.0f / (float)have;
;         float y[8];
; #pragma unroll
;         for (int e = 0; e < 8; ++e) y[e] = acc[e] * inv - vn[e];
;         *(GAS v4u*)(WSB(F, WS_BR) + (size_t)2 * M_PAD * D + (size_t)(rowbase + t) * D + ch * 8) = (v4u){pk2(y[0], y[1]), pk2(y[2], y[3]), pk2(y[4], y[5]), pk2(y[6], y[7])};
	v_lshlrev_b32_e32 v144, 16, v116
	v_and_b32_e32 v145, 0xffff0000, v116
	v_lshlrev_b32_e32 v146, 16, v117
	v_and_b32_e32 v147, 0xffff0000, v117
	v_lshlrev_b32_e32 v148, 16, v118
	v_and_b32_e32 v149, 0xffff0000, v118
	v_lshlrev_b32_e32 v150, 16, v119
	v_and_b32_e32 v151, 0xffff0000, v119
	v_lshlrev_b32_e32 v152, 16, v84
	v_and_b32_e32 v153, 0xffff0000, v84
	v_lshlrev_b32_e32 v154, 16, v85
	v_and_b32_e32 v155, 0xffff0000, v85
	v_lshlrev_b32_e32 v156, 16, v86
	v_and_b32_e32 v157, 0xffff0000, v86
	v_lshlrev_b32_e32 v158, 16, v87
	v_and_b32_e32 v159, 0xffff0000, v87
	s_mov_b64 exec, s[28:29]
	v_pk_add_f32 v[160:161], v[144:145], v[152:153] neg_lo:[0,1] neg_hi:[0,1]
	v_pk_add_f32 v[162:163], v[146:147], v[154:155] neg_lo:[0,1] neg_hi:[0,1]
	v_pk_add_f32 v[164:165], v[148:149], v[156:157] neg_lo:[0,1] neg_hi:[0,1]
	v_pk_add_f32 v[166:167], v[150:151], v[158:159] neg_lo:[0,1] neg_hi:[0,1]
	s_mov_b64 exec, -1
	v_lshlrev_b32_e32 v152, 16, v52
	v_and_b32_e32 v153, 0xffff0000, v52
	v_lshlrev_b32_e32 v154, 16, v53
	v_and_b32_e32 v155, 0xffff0000, v53
	v_lshlrev_b32_e32 v156, 16, v54
	v_and_b32_e32 v157, 0xffff0000, v54
	v_lshlrev_b32_e32 v158, 16, v55
	v_and_b32_e32 v159, 0xffff0000, v55
	s_mov_b64 exec, s[30:31]
	v_pk_add_f32 v[160:161], v[144:145], v[152:153] neg_lo:[0,1] neg_hi:[0,1]
	v_pk_add_f32 v[162:163], v[146:147], v[154:155] neg_lo:[0,1] neg_hi:[0,1]
	v_pk_add_f32 v[164:165], v[148:149], v[156:157] neg_lo:[0,1] neg_hi:[0,1]
	v_pk_add_f32 v[166:167], v[150:151], v[158:159] neg_lo:[0,1] neg_hi:[0,1]
	s_mov_b64 exec, -1
	v_pk_add_f32 v[8:9], v[8:9], v[160:161]
	v_pk_add_f32 v[10:11], v[10:11], v[162:163]
	v_pk_add_f32 v[12:13], v[12:13], v[164:165]
	v_pk_add_f32 v[14:15], v[14:15], v[166:167]
	v_pk_fma_f32 v[168:169], v[8:9], v[4:5], v[144:145] neg_lo:[0,0,1] neg_hi:[0,0,1]
	v_pk_fma_f32 v[170:171], v[10:11], v[4:5], v[146:147] neg_lo:[0,0,1] neg_hi:[0,0,1]
	v_pk_fma_f32 v[172:173], v[12:13], v[4:5], v[148:149] neg_lo:[0,0,1] neg_hi:[0,0,1]
	v_pk_fma_f32 v[174:175], v[14:15], v[4:5], v[150:151] neg_lo:[0,0,1] neg_hi:[0,0,1]
	v_cvt_pk_bf16_f32 v176, v168, v169
	v_cvt_pk_bf16_f32 v177, v170, v171
	v_cvt_pk_bf16_f32 v178, v172, v173
	v_cvt_pk_bf16_f32 v179, v174, v175
	s_nop 0
	global_store_dwordx4 v3, v[176:179], s[26:27] offset:2048
	s_nop 1
	s_waitcnt vmcnt(15)
	v_lshlrev_b32_e32 v144, 16, v120
	v_and_b32_e32 v145, 0xffff0000, v120
	v_lshlrev_b32_e32 v146, 16, v121
	v_and_b32_e32 v147, 0xffff0000, v121
	v_lshlrev_b32_e32 v148, 16, v122
	v_and_b32_e32 v149, 0xffff0000, v122
	v_lshlrev_b32_e32 v150, 16, v123
	v_and_b32_e32 v151, 0xffff0000, v123
	v_lshlrev_b32_e32 v152, 16, v88
	v_and_b32_e32 v153, 0xffff0000, v88
	v_lshlrev_b32_e32 v154, 16, v89
	v_and_b32_e32 v155, 0xffff0000, v89
	v_lshlrev_b32_e32 v156, 16, v90
	v_and_b32_e32 v157, 0xffff0000, v90
	v_lshlrev_b32_e32 v158, 16, v91
	v_and_b32_e32 v159, 0xffff0000, v91
	s_mov_b64 exec, s[28:29]
	v_pk_add_f32 v[160:161], v[144:145], v[152:153] neg_lo:[0,1] neg_hi:[0,1]
	v_pk_add_f32 v[162:163], v[146:147], v[154:155] neg_lo:[0,1] neg_hi:[0,1]
	v_pk_add_f32 v[164:165], v[148:149], v[156:157] neg_lo:[0,1] neg_hi:[0,1]
	v_pk_add_f32 v[166:167], v[150:151], v[158:159] neg_lo:[0,1] neg_hi:[0,1]
	s_mov_b64 exec, -1
	v_lshlrev_b32_e32 v152, 16, v56
	v_and_b32_e32 v153, 0xffff0000, v56
	v_lshlrev_b32_e32 v154, 16, v57
	v_and_b32_e32 v155, 0xffff0000, v57
	v_lshlrev_b32_e32 v156, 16, v58
	v_and_b32_e32 v157, 0xffff0000, v58
	v_lshlrev_b32_e32 v158, 16, v59
	v_and_b32_e32 v159, 0xffff0000, v59
	s_mov_b64 exec, s[30:31]
	v_pk_add_f32 v[160:161], v[144:145], v[152:153] neg_lo:[0,1] neg_hi:[0,1]
	v_pk_add_f32 v[162:163], v[146:147], v[154:155] neg_lo:[0,1] neg_hi:[0,1]
	v_pk_add_f32 v[164:165], v[148:149], v[156:157] neg_lo:[0,1] neg_hi:[0,1]
	v_pk_add_f32 v[166:167], v[150:151], v[158:159] neg_lo:[0,1] neg_hi:[0,1]
	s_mov_b64 exec, -1
	v_pk_add_f32 v[8:9], v[8:9], v[160:161]
	v_pk_add_f32 v[10:11], v[10:11], v[162:163]
	v_pk_add_f32 v[12:13], v[12:13], v[164:165]
	v_pk_add_f32 v[14:15], v[14:15], v[166:167]
	v_pk_fma_f32 v[168:169], v[8:9], v[4:5], v[144:145] neg_lo:[0,0,1] neg_hi:[0,0,1]
	v_pk_fma_f32 v[170:171], v[10:11], v[4:5], v[146:147] neg_lo:[0,0,1] neg_hi:[0,0,1]
	v_pk_fma_f32 v[172:173], v[12:13], v[4:5], v[148:149] neg_lo:[0,0,1] neg_hi:[0,0,1]
	v_pk_fma_f32 v[174:175], v[14:15], v[4:5], v[150:151] neg_lo:[0,0,1] neg_hi:[0,0,1]
	v_cvt_pk_bf16_f32 v176, v168, v169
	v_cvt_pk_bf16_f32 v177, v170, v171
	v_cvt_pk_bf16_f32 v178, v172, v173
	v_cvt_pk_bf16_f32 v179, v174, v175
	s_add_u32 s26, s22, 0x5000
	s_addc_u32 s27, s23, 0
	s_nop 0
	global_store_dwordx4 v3, v[176:179], s[26:27]
	s_nop 1
	s_waitcnt vmcnt(15)
; #define GAS __attribute__((address_space(1)))
; __device__ __forceinline__ unsigned pk2(float lo, float hi) { return f2bf(lo) | (f2bf(hi) << 16); }
; #define WSB(F, off) ((bf16*)(wsq((F).ws) + (off)))
; __device__ __forceinline__ void pool_unit(const Frame& F, int layer, int uid) {
;     ...
;     for (int tt = 0; tt < 16; ++tt) {
;         const int t = ts + tt;
;         float vn[8], vo[8]; pool_row(F, layer, stream, b, rowbase, t, ch, vn);
;         if (tt > 0) pool_row(F, layer, stream, b, rowbase, t - win, ch, vo);
; #pragma unroll
;         for (int e = 0; e < 8; ++e) acc[e] += vn[e] - (tt > 0 ? vo[e] : 0.f);
;         const int have = (stream == 2) ? (t + 1 < win ? t + 1 : win) : win;
;         const float inv = 1.0f / (float)have;
;         float y[8];
; #pragma unroll
;         for (int e = 0; e < 8; ++e) y[e] = acc[e] * inv - vn[e];
;         *(GAS v4u*)(WSB(F, WS_BR) + (size_t)2 * M_PAD * D + (size_t)(rowbase + t) * D + ch * 8) = (v4u){pk2(y[0], y[1]), pk2(y[2], y[3]), pk2(y[4], y[5]), pk2(y[6], y[7])};
	v_lshlrev_b32_e32 v144, 16, v124
	v_and_b32_e32 v145, 0xffff0000, v124
	v_lshlrev_b32_e32 v146, 16, v125
	v_and_b32_e32 v147, 0xffff0000, v125
	v_lshlrev_b32_e32 v148, 16, v126
	v_and_b32_e32 v149, 0xffff0000, v126
	v_lshlrev_b32_e32 v150, 16, v127
	v_and_b32_e32 v151, 0xffff0000, v127
	v_lshlrev_b32_e32 v152, 16, v92
	v_and_b32_e32 v153, 0xffff0000, v92
	v_lshlrev_b32_e32 v154, 16, v93
	v_and_b32_e32 v155, 0xffff0000, v93
	v_lshlrev_b32_e32 v156, 16, v94
	v_and_b32_e32 v157, 0xffff0000, v94
	v_lshlrev_b32_e32 v158, 16, v95
	v_and_b32_e32 v159, 0xffff0000, v95
	s_mov_b64 exec, s[28:29]
	v_pk_add_f32 v[160:161], v[144:145], v[152:153] neg_lo:[0,1] neg_hi:[0,1]
	v_pk_add_f32 v[162:163], v[146:147], v[154:155] neg_lo:[0,1] neg_hi:[0,1]
	v_pk_add_f32 v[164:165], v[148:149], v[156:157] neg_lo:[0,1] neg_hi:[0,1]
	v_pk_add_f32 v[166:167], v[150:151], v[158:159] neg_lo:[0,1] neg_hi:[0,1]
	s_mov_b64 exec, -1
	v_lshlrev_b32_e32 v152, 16, v60
	v_and_b32_e32 v153, 0xffff0000, v60
	v_lshlrev_b32_e32 v154, 16, v61
	v_and_b32_e32 v155, 0xffff0000, v61
	v_lshlrev_b32_e32 v156, 16, v62
	v_and_b32_e32 v157, 0xffff0000, v62
	v_lshlrev_b32_e32 v158, 16, v63
	v_and_b32_e32 v159, 0xffff0000, v63
	s_mov_b64 exec, s[30:31]
	v_pk_add_f32 v[160:161], v[144:145], v[152:153] neg_lo:[0,1] neg_hi:[0,1]
	v_pk_add_f32 v[162:163], v[146:147], v[154:155] neg_lo:[0,1] neg_hi:[0,1]
	v_pk_add_f32 v[164:165], v[148:149], v[156:157] neg_lo:[0,1] neg_hi:[0,1]
	v_pk_add_f32 v[166:167], v[150:151], v[158:159] neg_lo:[0,1] neg_hi:[0,1]
	s_mov_b64 exec, -1
	v_pk_add_f32 v[8:9], v[8:9], v[160:161]
	v_pk_add_f32 v[10:11], v[10:11], v[162:163]
	v_pk_add_f32 v[12:13], v[12:13], v[164:165]
	v_pk_add_f32 v[14:15], v[14:15], v[166:167]
	v_pk_fma_f32 v[168:169], v[8:9], v[4:5], v[144:145] neg_lo:[0,0,1] neg_hi:[0,0,1]
	v_pk_fma_f32 v[170:171], v[10:11], v[4:5], v[146:147] neg_lo:[0,0,1] neg_hi:[0,0,1]
	v_pk_fma_f32 v[172:173], v[12:13], v[4:5], v[148:149] neg_lo:[0,0,1] neg_hi:[0,0,1]
	v_pk_fma_f32 v[174:175], v[14:15], v[4:5], v[150:151] neg_lo:[0,0,1] neg_hi:[0,0,1]
	v_cvt_pk_bf16_f32 v176, v168, v169
	v_cvt_pk_bf16_f32 v177, v170, v171
	v_cvt_pk_bf16_f32 v178, v172, v173
	v_cvt_pk_bf16_f32 v179, v174, v175
	s_nop 0
	global_store_dwordx4 v3, v[176:179], s[26:27] offset:2048
	s_nop 1
	s_waitcnt vmcnt(15)
	v_lshlrev_b32_e32 v144, 16, v128
	v_and_b32_e32 v145, 0xffff0000, v128
	v_lshlrev_b32_e32 v146, 16, v129
	v_and_b32_e32 v147, 0xffff0000, v129
	v_lshlrev_b32_e32 v148, 16, v130
	v_and_b32_e32 v149, 0xffff0000, v130
	v_lshlrev_b32_e32 v150, 16, v131
	v_and_b32_e32 v151, 0xffff0000, v131
	v_lshlrev_b32_e32 v152, 16, v96
	v_and_b32_e32 v153, 0xffff0000, v96
	v_lshlrev_b32_e32 v154, 16, v97
	v_and_b32_e32 v155, 0xffff0000, v97
	v_lshlrev_b32_e32 v156, 16, v98
	v_and_b32_e32 v157, 0xffff0000, v98
	v_lshlrev_b32_e32 v158, 16, v99
	v_and_b32_e32 v159, 0xffff0000, v99
	s_mov_b64 exec, s[28:29]
	v_pk_add_f32 v[160:161], v[144:145], v[152:153] neg_lo:[0,1] neg_hi:[0,1]
	v_pk_add_f32 v[162:163], v[146:147], v[154:155] neg_lo:[0,1] neg_hi:[0,1]
	v_pk_add_f32 v[164:165], v[148:149], v[156:157] neg_lo:[0,1] neg_hi:[0,1]
	v_pk_add_f32 v[166:167], v[150:151], v[158:159] neg_lo:[0,1] neg_hi:[0,1]
	s_mov_b64 exec, -1
	v_lshlrev_b32_e32 v152, 16, v64
	v_and_b32_e32 v153, 0xffff0000, v64
	v_lshlrev_b32_e32 v154, 16, v65
	v_and_b32_e32 v155, 0xffff0000, v65
	v_lshlrev_b32_e32 v156, 16, v66
	v_and_b32_e32 v157, 0xffff0000, v66
	v_lshlrev_b32_e32 v158, 16, v67
	v_and_b32_e32 v159, 0xffff0000, v67
	s_mov_b64 exec, s[30:31]
	v_pk_add_f32 v[160:161], v[144:145], v[152:153] neg_lo:[0,1] neg_hi:[0,1]
	v_pk_add_f32 v[162:163], v[146:147], v[154:155] neg_lo:[0,1] neg_hi:[0,1]
	v_pk_add_f32 v[164:165], v[148:149], v[156:157] neg_lo:[0,1] neg_hi:[0,1]
	v_pk_add_f32 v[166:167], v[150:151], v[158:159] neg_lo:[0,1] neg_hi:[0,1]
	s_mov_b64 exec, -1
	v_pk_add_f32 v[8:9], v[8:9], v[160:161]
	v_pk_add_f32 v[10:11], v[10:11], v[162:163]
	v_pk_add_f32 v[12:13], v[12:13], v[164:165]
	v_pk_add_f32 v[14:15], v[14:15], v[166:167]
	v_pk_fma_f32 v[168:169], v[8:9], v[4:5], v[144:145] neg_lo:[0,0,1] neg_hi:[0,0,1]
	v_pk_fma_f32 v[170:171], v[10:11], v[4:5], v[146:147] neg_lo:[0,0,1] neg_hi:[0,0,1]
	v_pk_fma_f32 v[172:173], v[12:13], v[4:5], v[148:149] neg_lo:[0,0,1] neg_hi:[0,0,1]
	v_pk_fma_f32 v[174:175], v[14:15], v[4:5], v[150:151] neg_lo:[0,0,1] neg_hi:[0,0,1]
	v_cvt_pk_bf16_f32 v176, v168, v169
	v_cvt_pk_bf16_f32 v177, v170, v171
	v_cvt_pk_bf16_f32 v178, v172, v173
	v_cvt_pk_bf16_f32 v179, v174, v175
	s_add_u32 s26, s22, 0x6000
	s_addc_u32 s27, s23, 0
	s_nop 0
	global_store_dwordx4 v3, v[176:179], s[26:27]
	s_nop 1
	s_waitcnt vmcnt(15)
; #define GAS __attribute__((address_space(1)))
; __device__ __forceinline__ unsigned pk2(float lo, float hi) { return f2bf(lo) | (f2bf(hi) << 16); }
; #define WSB(F, off) ((bf16*)(wsq((F).ws) + (off)))
; __device__ __forceinline__ void pool_unit(const Frame& F, int layer, int uid) {
;     ...
;     for (int tt = 0; tt < 16; ++tt) {
;         const int t = ts + tt;
;         float vn[8], vo[8]; pool_row(F, layer, stream, b, rowbase, t, ch, vn);
;         if (tt > 0) pool_row(F, layer, stream, b, rowbase, t - win, ch, vo);
; #pragma unroll
;         for (int e = 0; e < 8; ++e) acc[e] += vn[e] - (tt > 0 ? vo[e] : 0.f);
;         const int have = (stream == 2) ? (t + 1 < win ? t + 1 : win) : win;
;         const float inv = 1.0f / (float)have;
;         float y[8];
; #pragma unroll
;         for (int e = 0; e < 8; ++e) y[e] = acc[e] * inv - vn[e];
;         *(GAS v4u*)(WSB(F, WS_BR) + (size_t)2 * M_PAD * D + (size_t)(rowbase + t) * D + ch * 8) = (v4u){pk2(y[0], y[1]), pk2(y[2], y[3]), pk2(y[4], y[5]), pk2(y[6], y[7])};
	v_lshlrev_b32_e32 v144, 16, v132
	v_and_b32_e32 v145, 0xffff0000, v132
	v_lshlrev_b32_e32 v146, 16, v133
	v_and_b32_e32 v147, 0xffff0000, v133
	v_lshlrev_b32_e32 v148, 16, v134
	v_and_b32_e32 v149, 0xffff0000, v134
	v_lshlrev_b32_e32 v150, 16, v135
	v_and_b32_e32 v151, 0xffff0000, v135
	v_lshlrev_b32_e32 v152, 16, v100
	v_and_b32_e32 v153, 0xffff0000, v100
	v_lshlrev_b32_e32 v154, 16, v101
	v_and_b32_e32 v155, 0xffff0000, v101
	v_lshlrev_b32_e32 v156, 16, v102
	v_and_b32_e32 v157, 0xffff0000, v102
	v_lshlrev_b32_e32 v158, 16, v103
	v_and_b32_e32 v159, 0xffff0000, v103
	s_mov_b64 exec, s[28:29]
	v_pk_add_f32 v[160:161], v[144:145], v[152:153] neg_lo:[0,1] neg_hi:[0,1]
	v_pk_add_f32 v[162:163], v[146:147], v[154:155] neg_lo:[0,1] neg_hi:[0,1]
	v_pk_add_f32 v[164:165], v[148:149], v[156:157] neg_lo:[0,1] neg_hi:[0,1]
	v_pk_add_f32 v[166:167], v[150:151], v[158:159] neg_lo:[0,1] neg_hi:[0,1]
	s_mov_b64 exec, -1
	v_lshlrev_b32_e32 v152, 16, v68
	v_and_b32_e32 v153, 0xffff0000, v68
	v_lshlrev_b32_e32 v154, 16, v69
	v_and_b32_e32 v155, 0xffff0000, v69
	v_lshlrev_b32_e32 v156, 16, v70
	v_and_b32_e32 v157, 0xffff0000, v70
	v_lshlrev_b32_e32 v158, 16, v71
	v_and_b32_e32 v159, 0xffff0000, v71
	s_mov_b64 exec, s[30:31]
	v_pk_add_f32 v[160:161], v[144:145], v[152:153] neg_lo:[0,1] neg_hi:[0,1]
	v_pk_add_f32 v[162:163], v[146:147], v[154:155] neg_lo:[0,1] neg_hi:[0,1]
	v_pk_add_f32 v[164:165], v[148:149], v[156:157] neg_lo:[0,1] neg_hi:[0,1]
	v_pk_add_f32 v[166:167], v[150:151], v[158:159] neg_lo:[0,1] neg_hi:[0,1]
	s_mov_b64 exec, -1
	v_pk_add_f32 v[8:9], v[8:9], v[160:161]
	v_pk_add_f32 v[10:11], v[10:11], v[162:163]
	v_pk_add_f32 v[12:13], v[12:13], v[164:165]
	v_pk_add_f32 v[14:15], v[14:15], v[166:167]
	v_pk_fma_f32 v[168:169], v[8:9], v[4:5], v[144:145] neg_lo:[0,0,1] neg_hi:[0,0,1]
	v_pk_fma_f32 v[170:171], v[10:11], v[4:5], v[146:147] neg_lo:[0,0,1] neg_hi:[0,0,1]
	v_pk_fma_f32 v[172:173], v[12:13], v[4:5], v[148:149] neg_lo:[0,0,1] neg_hi:[0,0,1]
	v_pk_fma_f32 v[174:175], v[14:15], v[4:5], v[150:151] neg_lo:[0,0,1] neg_hi:[0,0,1]
	v_cvt_pk_bf16_f32 v176, v168, v169
	v_cvt_pk_bf16_f32 v177, v170, v171
	v_cvt_pk_bf16_f32 v178, v172, v173
	v_cvt_pk_bf16_f32 v179, v174, v175
	s_nop 0
	global_store_dwordx4 v3, v[176:179], s[26:27] offset:2048
	s_nop 1
	s_waitcnt vmcnt(15)
	v_lshlrev_b32_e32 v144, 16, v136
	v_and_b32_e32 v145, 0xffff0000, v136
	v_lshlrev_b32_e32 v146, 16, v137
	v_and_b32_e32 v147, 0xffff0000, v137
	v_lshlrev_b32_e32 v148, 16, v138
	v_and_b32_e32 v149, 0xffff0000, v138
	v_lshlrev_b32_e32 v150, 16, v139
	v_and_b32_e32 v151, 0xffff0000, v139
	v_lshlrev_b32_e32 v152, 16, v104
	v_and_b32_e32 v153, 0xffff0000, v104
	v_lshlrev_b32_e32 v154, 16, v105
	v_and_b32_e32 v155, 0xffff0000, v105
	v_lshlrev_b32_e32 v156, 16, v106
	v_and_b32_e32 v157, 0xffff0000, v106
	v_lshlrev_b32_e32 v158, 16, v107
	v_and_b32_e32 v159, 0xffff0000, v107
	s_mov_b64 exec, s[28:29]
	v_pk_add_f32 v[160:161], v[144:145], v[152:153] neg_lo:[0,1] neg_hi:[0,1]
	v_pk_add_f32 v[162:163], v[146:147], v[154:155] neg_lo:[0,1] neg_hi:[0,1]
	v_pk_add_f32 v[164:165], v[148:149], v[156:157] neg_lo:[0,1] neg_hi:[0,1]
	v_pk_add_f32 v[166:167], v[150:151], v[158:159] neg_lo:[0,1] neg_hi:[0,1]
	s_mov_b64 exec, -1
	v_lshlrev_b32_e32 v152, 16, v72
	v_and_b32_e32 v153, 0xffff0000, v72
	v_lshlrev_b32_e32 v154, 16, v73
	v_and_b32_e32 v155, 0xffff0000, v73
	v_lshlrev_b32_e32 v156, 16, v74
	v_and_b32_e32 v157, 0xffff0000, v74
	v_lshlrev_b32_e32 v158, 16, v75
	v_and_b32_e32 v159, 0xffff0000, v75
	s_mov_b64 exec, s[30:31]
	v_pk_add_f32 v[160:161], v[144:145], v[152:153] neg_lo:[0,1] neg_hi:[0,1]
	v_pk_add_f32 v[162:163], v[146:147], v[154:155] neg_lo:[0,1] neg_hi:[0,1]
	v_pk_add_f32 v[164:165], v[148:149], v[156:157] neg_lo:[0,1] neg_hi:[0,1]
	v_pk_add_f32 v[166:167], v[150:151], v[158:159] neg_lo:[0,1] neg_hi:[0,1]
	s_mov_b64 exec, -1
	v_pk_add_f32 v[8:9], v[8:9], v[160:161]
	v_pk_add_f32 v[10:11], v[10:11], v[162:163]
	v_pk_add_f32 v[12:13], v[12:13], v[164:165]
	v_pk_add_f32 v[14:15], v[14:15], v[166:167]
	v_pk_fma_f32 v[168:169], v[8:9], v[4:5], v[144:145] neg_lo:[0,0,1] neg_hi:[0,0,1]
	v_pk_fma_f32 v[170:171], v[10:11], v[4:5], v[146:147] neg_lo:[0,0,1] neg_hi:[0,0,1]
	v_pk_fma_f32 v[172:173], v[12:13], v[4:5], v[148:149] neg_lo:[0,0,1] neg_hi:[0,0,1]
	v_pk_fma_f32 v[174:175], v[14:15], v[4:5], v[150:151] neg_lo:[0,0,1] neg_hi:[0,0,1]
	v_cvt_pk_bf16_f32 v176, v168, v169
	v_cvt_pk_bf16_f32 v177, v170, v171
	v_cvt_pk_bf16_f32 v178, v172, v173
	v_cvt_pk_bf16_f32 v179, v174, v175
	s_add_u32 s26, s22, 0x7000
	s_addc_u32 s27, s23, 0
	s_nop 0
	global_store_dwordx4 v3, v[176:179], s[26:27]
	s_nop 1
	s_waitcnt vmcnt(15)
	v_lshlrev_b32_e32 v144, 16, v140
	v_and_b32_e32 v145, 0xffff0000, v140
	v_lshlrev_b32_e32 v146, 16, v141
	v_and_b32_e32 v147, 0xffff0000, v141
	v_lshlrev_b32_e32 v148, 16, v142
	v_and_b32_e32 v149, 0xffff0000, v142
	v_lshlrev_b32_e32 v150, 16, v143
	v_and_b32_e32 v151, 0xffff0000, v143
	v_lshlrev_b32_e32 v152, 16, v108
	v_and_b32_e32 v153, 0xffff0000, v108
	v_lshlrev_b32_e32 v154, 16, v109
	v_and_b32_e32 v155, 0xffff0000, v109
	v_lshlrev_b32_e32 v156, 16, v110
	v_and_b32_e32 v157, 0xffff0000, v110
	v_lshlrev_b32_e32 v158, 16, v111
	v_and_b32_e32 v159, 0xffff0000, v111
	s_mov_b64 exec, s[28:29]
	v_pk_add_f32 v[160:161], v[144:145], v[152:153] neg_lo:[0,1] neg_hi:[0,1]
	v_pk_add_f32 v[162:163], v[146:147], v[154:155] neg_lo:[0,1] neg_hi:[0,1]
	v_pk_add_f32 v[164:165], v[148:149], v[156:157] neg_lo:[0,1] neg_hi:[0,1]
	v_pk_add_f32 v[166:167], v[150:151], v[158:159] neg_lo:[0,1] neg_hi:[0,1]
	s_mov_b64 exec, -1
	v_lshlrev_b32_e32 v152, 16, v76
	v_and_b32_e32 v153, 0xffff0000, v76
	v_lshlrev_b32_e32 v154, 16, v77
	v_and_b32_e32 v155, 0xffff0000, v77
	v_lshlrev_b32_e32 v156, 16, v78
	v_and_b32_e32 v157, 0xffff0000, v78
	v_lshlrev_b32_e32 v158, 16, v79
	v_and_b32_e32 v159, 0xffff0000, v79
	s_mov_b64 exec, s[30:31]
	v_pk_add_f32 v[160:161], v[144:145], v[152:153] neg_lo:[0,1] neg_hi:[0,1]
	v_pk_add_f32 v[162:163], v[146:147], v[154:155] neg_lo:[0,1] neg_hi:[0,1]
	v_pk_add_f32 v[164:165], v[148:149], v[156:157] neg_lo:[0,1] neg_hi:[0,1]
	v_pk_add_f32 v[166:167], v[150:151], v[158:159] neg_lo:[0,1] neg_hi:[0,1]
	s_mov_b64 exec, -1
	v_pk_add_f32 v[8:9], v[8:9], v[160:161]
	v_pk_add_f32 v[10:11], v[10:11], v[162:163]
	v_pk_add_f32 v[12:13], v[12:13], v[164:165]
	v_pk_add_f32 v[14:15], v[14:15], v[166:167]
	v_pk_fma_f32 v[168:169], v[8:9], v[4:5], v[144:145] neg_lo:[0,0,1] neg_hi:[0,0,1]
	v_pk_fma_f32 v[170:171], v[10:11], v[4:5], v[146:147] neg_lo:[0,0,1] neg_hi:[0,0,1]
	v_pk_fma_f32 v[172:173], v[12:13], v[4:5], v[148:149] neg_lo:[0,0,1] neg_hi:[0,0,1]
	v_pk_fma_f32 v[174:175], v[14:15], v[4:5], v[150:151] neg_lo:[0,0,1] neg_hi:[0,0,1]
	v_cvt_pk_bf16_f32 v176, v168, v169
	v_cvt_pk_bf16_f32 v177, v170, v171
	v_cvt_pk_bf16_f32 v178, v172, v173
	v_cvt_pk_bf16_f32 v179, v174, v175
	s_nop 0
	global_store_dwordx4 v3, v[176:179], s[26:27] offset:2048
	s_nop 1
; __device__ __forceinline__ void pool_unit(const Frame& F, int layer, int uid) {
;     int stream, b, t0, Tlen, rowbase;
;     if (uid < 1024) { stream = 0; b = uid >> 5; t0 = (uid & 31) * 64; Tlen = T; rowbase = b * T; }
;     else if (uid < 1032) { stream = 1; b = uid - 1024; t0 = 0; Tlen = ST; rowbase = ROW_S + b * ST; }
;     else { stream = 2; b = 0; t0 = 0; Tlen = NMETA; rowbase = ROW_M; }
; __global__ void __launch_bounds__(512, 2) mega_fwd(Args args) {
;     ...
;               else if (qk == 1 || qk == 4) { pool_unit(F, l, qk == 1 ? 1024 + u : u); if (qk == 1) chain_signal(F, ch, 0); }
.Lpool_fast_done:
	s_mov_b64 exec, -1
	s_branch .LBB0_1354
.Lpool_small_rows:
	s_add_i32 s10, s5, 0x400
	s_cmp_eq_u32 s3, 1
	s_cselect_b64 s[14:15], -1, 0
	s_and_b64 s[8:9], s[14:15], exec
	s_cselect_b32 s13, s10, s5
	s_cmpk_lt_i32 s13, 0x400
	s_cselect_b64 s[16:17], -1, 0
	s_cmpk_gt_i32 s13, 0x3ff
	s_mov_b64 s[10:11], -1
	s_cbranch_scc0 .LBB0_1197
	s_cmpk_gt_u32 s13, 0x407
	s_mov_b64 s[10:11], 0
	s_cbranch_scc1 .LBB0_1497
	s_add_i32 s28, s13, 0xfffffc00
	s_lshl_b32 s3, s28, 5
	s_add_i32 s3, s3, 0x10000
	s_mov_b32 s12, 32
	s_mov_b64 s[18:19], 0
	s_mov_b64 s[8:9], -1
